# deterministic ssq slot stores instead of float atomics; pipelined x1 phase
# speedup vs baseline: 1.0101x; 1.0101x over previous
; #define LAS __attribute__((address_space(3)))
; __device__ __forceinline__ KP kernarg_params() { KP p = (KP)__builtin_amdgcn_kernarg_segment_ptr(); asm volatile("" : "+s"(p)); return p; }
; __global__ void __launch_bounds__(512, 2) fwd_megakernel(Params Pval) {
;     ...
;     cg::grid_group grid = cg::this_grid();
;     pg8::StaticOrder S;
;     const int ph_lo = kernarg_params()->ph_lo, ph_hi = kernarg_params()->ph_hi;
;     unsigned char* ws0 = kernarg_params()->ws;
;     volatile LAS unsigned* stw = (volatile LAS unsigned*)(lds + LDS_BYTES - 16);
;     if (threadIdx.x == 0) { stw[0] = 0u; stw[1] = 0u; }
;     __syncthreads();
;     const XcdBarrier xbar = xcd_barrier_post((unsigned*)(ws0 + OFF_BAR), stw);
;     int rep = 0; (void)rep;
;     for (int ph = ph_lo; ph < ph_hi; ++ph) {
.LBB0_5:
	s_or_b64 exec, exec, s[4:5]
	v_readlane_b32 s1, v254, 0
	s_cmp_ge_i32 s39, s1
	s_cbranch_scc1 .LBB0_591
	s_cmpk_lt_i32 s2, 0x200
	s_cselect_b64 s[4:5], -1, 0
	v_writelane_b32 v254, s4, 9
	s_lshl_b32 s3, s2, 9
	s_ashr_i32 s38, s2, 31
	v_writelane_b32 v254, s5, 10
	v_writelane_b32 v254, s3, 11
	s_lshr_b32 s3, s38, 29
	s_add_i32 s3, s2, s3
	s_ashr_i32 s4, s3, 3
	s_and_b32 s3, s3, -8
	s_mov_b32 s21, 0
	s_mov_b32 s20, s2
	v_writelane_b32 v254, s4, 12
	s_sub_i32 s6, s2, s3
	s_lshl_b32 s7, s2, 3
	s_lshl_b64 s[4:5], s[20:21], 9
	v_writelane_b32 v254, s4, 13
	s_cmp_lg_u32 s39, 0
	v_lshrrev_b32_e32 v1, 20, v0
	v_writelane_b32 v254, s5, 14
	s_cselect_b64 s[4:5], -1, 0
	v_writelane_b32 v254, s4, 15
	v_lshrrev_b32_e32 v0, 10, v0
	v_or_b32_e32 v0, v0, v1
	v_writelane_b32 v254, s5, 16
	s_movk_i32 s3, 0x3ff
	v_readlane_b32 s4, v254, 1
	v_readlane_b32 s5, v254, 2
	s_cmp_eq_u32 s0, 15
	v_and_or_b32 v0, v0, s3, v208
	s_load_dword s3, s[4:5], 0x98
	s_cselect_b64 s[4:5], -1, 0
	v_writelane_b32 v254, s4, 17
	s_cmp_eq_u32 s0, 14
	s_mul_i32 s1, s55, s54
	v_writelane_b32 v254, s5, 18
	s_cselect_b64 s[4:5], -1, 0
	v_writelane_b32 v254, s4, 19
	s_cmp_eq_u32 s0, 13
	s_waitcnt lgkmcnt(0)
	s_mul_i32 s53, s1, s3
	v_writelane_b32 v254, s5, 20
	s_cselect_b64 s[4:5], -1, 0
	v_writelane_b32 v254, s4, 21
	s_cmp_eq_u32 s0, 12
	s_movk_i32 s55, 0x1100
	v_writelane_b32 v254, s5, 22
	s_cselect_b64 s[4:5], -1, 0
	v_writelane_b32 v254, s4, 23
	s_cmp_eq_u32 s0, 11
	v_mbcnt_lo_u32_b32 v1, -1, 0
	v_writelane_b32 v254, s5, 24
	s_cselect_b64 s[4:5], -1, 0
	v_writelane_b32 v254, s4, 25
	s_cmp_eq_u32 s0, 10
	v_mbcnt_hi_u32_b32 v212, -1, v1
	v_writelane_b32 v254, s5, 26
	s_cselect_b64 s[4:5], -1, 0
	v_writelane_b32 v254, s4, 27
	s_cmp_eq_u32 s0, 9
	v_and_b32_e32 v213, 64, v212
	v_writelane_b32 v254, s5, 28
	s_cselect_b64 s[4:5], -1, 0
	v_writelane_b32 v254, s4, 29
	s_cmp_eq_u32 s0, 8
	v_mov_b32_e32 v169, 0
	v_writelane_b32 v254, s5, 30
	s_cselect_b64 s[4:5], -1, 0
	v_writelane_b32 v254, s4, 31
	s_cmp_eq_u32 s0, 7
	s_mov_b32 s42, 0x1c000
	v_writelane_b32 v254, s5, 32
	s_cselect_b64 s[4:5], -1, 0
	v_writelane_b32 v254, s4, 33
	s_cmp_eq_u32 s0, 6
	s_movk_i32 s80, 0x90
	v_writelane_b32 v254, s5, 34
	s_cselect_b64 s[4:5], -1, 0
	v_writelane_b32 v254, s4, 35
	s_cmp_eq_u32 s0, 5
	s_mov_b32 s43, 0xc000
	v_writelane_b32 v254, s5, 36
	s_cselect_b64 s[4:5], -1, 0
	v_writelane_b32 v254, s4, 37
	s_cmp_eq_u32 s0, 4
	s_mov_b32 s66, 0x4400000
	v_writelane_b32 v254, s5, 38
	s_cselect_b64 s[4:5], -1, 0
	v_writelane_b32 v254, s4, 39
	s_cmp_eq_u32 s0, 3
	s_mov_b32 s67, 0x20000
	v_writelane_b32 v254, s5, 40
	s_cselect_b64 s[4:5], -1, 0
	v_writelane_b32 v254, s4, 41
	s_cmp_eq_u32 s0, 2
	s_mov_b32 s44, 0x3e000
	v_writelane_b32 v254, s5, 42
	s_cselect_b64 s[4:5], -1, 0
	v_writelane_b32 v254, s4, 43
	s_cmp_eq_u32 s0, 1
	s_movk_i32 s68, 0x1000
	v_writelane_b32 v254, s5, 44
	s_cselect_b64 s[4:5], -1, 0
	v_writelane_b32 v254, s4, 45
	s_cmp_eq_u32 s0, 0
	s_movk_i32 s69, 0x2000
	v_writelane_b32 v254, s5, 46
	s_cselect_b64 s[4:5], -1, 0
	v_writelane_b32 v254, s4, 47
	s_lshl_b32 s3, s0, 6
	s_lshr_b32 s0, s6, 31
	v_writelane_b32 v254, s5, 48
	v_writelane_b32 v254, s6, 49
	v_writelane_b32 v254, s0, 50
	s_lshl_b32 s0, s2, 10
	v_writelane_b32 v254, s0, 51
	s_lshl_b32 s0, s2, 12
	v_writelane_b32 v254, s0, 52
	s_lshl_b32 s0, s2, 5
	v_writelane_b32 v254, s0, 53
	s_lshl_b32 s0, s2, 7
	v_writelane_b32 v254, s0, 54
	v_writelane_b32 v254, s7, 55
	s_add_i32 s0, s7, 0xfffff300
	v_writelane_b32 v254, s0, 56
	s_lshl_b64 s[0:1], s[20:21], 12
	s_add_u32 s0, s0, 0x2700000
	v_writelane_b32 v254, s0, 57
	s_addc_u32 s0, s1, 0
	v_writelane_b32 v254, s0, 58
	s_add_i32 s0, 0, 0x4800
	v_writelane_b32 v254, s0, 59
	s_add_i32 s0, 0, 0x1d000
	v_writelane_b32 v254, s0, 60
	s_lshl_b32 s0, s3, 2
	v_writelane_b32 v254, s0, 61
	s_add_i32 s1, 0, 0x8400
	v_writelane_b32 v254, s1, 62
	s_add_i32 s1, 0, 0x7400
	v_writelane_b32 v254, s1, 63
	s_add_i32 s1, 0, 0x6400
	v_writelane_b32 v255, s1, 0
	s_add_i32 s1, 0, 0x5400
	v_writelane_b32 v255, s1, 1
	s_add_i32 s1, 0, 0x25400
	v_writelane_b32 v255, s1, 2
	s_add_i32 s1, 0, 0x25404
	v_writelane_b32 v255, s1, 3
	v_cmp_eq_u32_e64 s[4:5], 0, v0
	s_add_i32 s78, 0, 0x1c000
	v_mov_b32_e32 v209, 0x358637bd
	v_writelane_b32 v255, s4, 4
	v_mov_b32_e32 v210, 0x3ecc95a3
	v_mov_b32_e32 v211, 1
	v_writelane_b32 v255, s5, 5
	s_lshl_b64 s[4:5], s[20:21], 13
	v_writelane_b32 v255, s4, 6
	v_xor_b32_e32 v214, 16, v212
	v_add_u32_e32 v215, 64, v213
	v_writelane_b32 v255, s5, 7
	v_writelane_b32 v255, s54, 8
	v_xor_b32_e32 v216, 32, v212
	v_mov_b32_e32 v217, 0x44000
	v_writelane_b32 v255, s55, 9
	v_mov_b32_e32 v218, 0x55000
	v_mov_b32_e32 v219, 0x66000
	v_mov_b32_e32 v220, 0x7fffd100
	v_mov_b32_e32 v170, 0x3f317218
	v_mov_b32_e32 v221, 0x7f800000
	v_mov_b32_e32 v222, 0x7fc00000
	v_mov_b32_e32 v223, 0xff800000
	v_mov_b32_e32 v224, 0x500
	s_movk_i32 s70, 0x3000
	s_mov_b32 s52, 0x42200000
	s_movk_i32 s0, 0x2200
	s_mov_b32 s77, 0x22000
	s_movk_i32 s45, 0x4000
	s_movk_i32 s46, 0x6000
	s_mov_b32 s81, 0x800000
	s_mov_b32 s71, 0x8000
	s_movk_i32 s72, 0x7fff
	s_mov_b32 s47, 0xa000
	s_mov_b32 s48, 0xe000
	s_mov_b32 s49, 0x10000
	s_mov_b32 s50, 0x12000
	s_mov_b32 s51, 0x14000
	s_mov_b32 s56, 0x16000
	s_mov_b32 s57, 0x18000
	s_mov_b32 s58, 0x1a000
	s_mov_b32 s59, 0x1e000
	s_mov_b32 s60, 0x2c000
	s_mov_b32 s61, 0x2e000
	s_mov_b32 s62, 0x30000
	s_mov_b32 s63, 0x3f000
	s_movk_i32 s64, 0x10ff
	s_mov_b32 s65, 0x24000
	s_mov_b32 s73, 0x26000
	s_mov_b32 s74, 0x28000
	s_mov_b32 s75, 0x2a000
	s_mov_b32 s76, 0x32000
	s_mov_b32 s79, 0x34000
	s_mov_b32 s92, 0x36000
	s_mov_b32 s94, 0x38000
	s_mov_b32 s95, 0x3a000
	s_mov_b64 s[82:83], 0x1400
	s_mov_b64 s[84:85], 0x2800
	s_mov_b64 s[86:87], 0x3c00
	s_mov_b64 s[88:89], 0x80
	v_writelane_b32 v255, s53, 10
	s_mov_b32 s4, 0
	v_writelane_b32 v255, s4, 40
	s_branch .LBB0_11

; __device__ __forceinline__ KP kernarg_params() { KP p = (KP)__builtin_amdgcn_kernarg_segment_ptr(); asm volatile("" : "+s"(p)); return p; }
; __global__ void __launch_bounds__(512, 2) fwd_megakernel(Params Pval) {
;     ...
;     for (int ph = ph_lo; ph < ph_hi; ++ph) {
;         const KP P = kernarg_params(); unsigned char* ws = P->ws;
;         if (ph == 0) phase_prologue(P, lds);
;         else {
;             const int layer = (ph - 1) / 7, sub = (ph - 1) % 7;
;             if (sub == 0 || sub == 4 || sub == 6) {
.LBB0_11:
	v_readlane_b32 s36, v254, 1
	v_readlane_b32 s37, v254, 2
	s_waitcnt lgkmcnt(0)
	s_load_dwordx2 s[90:91], s[36:37], 0x80
	v_readlane_b32 s4, v255, 40
	s_cmp_lg_u32 s4, 1
	s_cbranch_scc1 .Lmini_skip
	s_waitcnt lgkmcnt(0)
	s_add_u32 s8, s90, 0x8700000
	s_addc_u32 s9, s91, 0
	s_add_u32 s10, s8, 0x20000
	s_addc_u32 s11, s9, 0
	s_add_u32 s12, s8, 0x40000
	s_addc_u32 s13, s9, 0
	s_add_u32 s14, s8, 0x60000
	s_addc_u32 s15, s9, 0
	s_lshl_b32 s1, s54, 7
	s_mov_b32 s3, 0x8000
	v_lshl_add_u32 v0, s2, 9, v208
	v_lshrrev_b32_e32 v1, 2, v0
	v_and_b32_e32 v2, 3, v0
	v_lshlrev_b32_e32 v2, 19, v2
	s_mov_b64 s[6:7], exec
	v_cmp_gt_u32_e32 vcc, s3, v1
	s_and_b64 exec, exec, vcc
	s_cbranch_execz .Lmini_done
.Lmini_loop:
	v_lshl_add_u32 v3, v1, 2, v2
	global_load_dword v4, v3, s[8:9]
	global_load_dword v5, v3, s[10:11]
	global_load_dword v6, v3, s[12:13]
	global_load_dword v7, v3, s[14:15]
	s_waitcnt vmcnt(0)
	v_add_f32_e32 v4, v4, v5
	v_add_f32_e32 v4, v4, v6
	v_add_f32_e32 v4, v4, v7
	s_nop 1
	v_add_f32_dpp v4, v4, v4 quad_perm:[1,0,3,2] row_mask:0xf bank_mask:0xf
	s_nop 1
	v_add_f32_dpp v4, v4, v4 quad_perm:[2,3,0,1] row_mask:0xf bank_mask:0xf
	v_cmp_eq_u32_e32 vcc, 0, v2
	s_and_saveexec_b64 s[40:41], vcc
	global_store_dword v3, v4, s[8:9]
	s_mov_b64 exec, s[40:41]
	v_add_u32_e32 v1, s1, v1
	v_cmp_gt_u32_e32 vcc, s3, v1
	s_and_b64 exec, exec, vcc
	s_cbranch_execnz .Lmini_loop
.Lmini_done:
	s_mov_b64 exec, s[6:7]
	s_mov_b32 s4, 2
	s_nop 0
	v_writelane_b32 v255, s4, 40
	s_branch .LBB0_534
.Lmini_skip:
	s_cmp_lg_u32 s39, 0
	s_mov_b64 s[4:5], -1
	s_cbranch_scc0 .LBB0_357
	s_add_i32 s1, s39, -1
	s_mul_hi_i32 s3, s1, 0x92492493
	s_add_i32 s3, s3, s1
	s_lshr_b32 s4, s3, 31
	s_ashr_i32 s3, s3, 2
	s_add_i32 s94, s3, s4
	s_mul_i32 s3, s94, 7
	s_sub_i32 s93, s1, s3
	s_cmp_lt_i32 s93, 3
	v_writelane_b32 v255, s39, 11
	s_cbranch_scc1 .LBB0_16
	s_cmp_gt_i32 s93, 3
	s_cbranch_scc0 .LBB0_17
	s_cmp_gt_i32 s93, 5
	s_cbranch_scc0 .LBB0_18
	s_cmp_lg_u32 s93, 6
	s_mov_b64 s[96:97], -1
	s_cselect_b64 s[98:99], -1, 0
	s_cbranch_execz .LBB0_19
	s_branch .LBB0_20

; __device__ __forceinline__ int opaque_nblk() { int g = (int)gridDim.x; asm volatile("" : "+s"(g)); return g; }
; __device__ __forceinline__ int opaque_tid() { int t = threadIdx.x; asm volatile("" : "+v"(t)); return t; }
; __device__ void phase_x1(KP P, int layer) {
;     const int tid = opaque_tid(), lane = tid & 63; const int gw = blockIdx.x * 8 + (tid >> 6), nw = opaque_nblk() * 8;
;     const bf16_t* xin = (const bf16_t*)(P->ws + OFF_XB); const bf16_t* mix = (const bf16_t*)P->out; const float* ssq2 = (const float*)(P->ws + OFF_SSQ2);
;     float* ssq = (float*)(P->ws + OFF_SSQ);
;     bf16_t* x1b = (bf16_t*)(P->ws + OFF_PROJ); const float* nwp = P->norm_post + layer * 1024;
;     f32x4 wv[2][2];
; #pragma unroll
;     for (int i = 0; i < 2; ++i) { wv[i][0] = *(const f32x4*)(nwp + lane * 8 + 512 * i); wv[i][1] = *(const f32x4*)(nwp + lane * 8 + 512 * i + 4); }
; #pragma unroll 8
;     for (int row = gw; row < MTOK; row += nw) {
;         const float rstd = rsqrtf(ssq2[row] * (1.f / 1024.f) + EPS);
;         if (lane == 0) ssq[row] = 0.f;
; #pragma unroll
;         for (int i = 0; i < 2; ++i) { const size_t off = (size_t)row * 1024 + lane * 8 + 512 * i;
;             float xv[8], mv[8]; unpack8(__builtin_nontemporal_load((const u32x4*)(xin + off)), xv); unpack8(__builtin_nontemporal_load((const u32x4*)(mix + off)), mv);
.LBB0_85:
	s_and_b64 vcc, exec, s[98:99]
	s_cbranch_vccz .LBB0_92
	s_cmpk_lg_u32 s54, 0x100
	s_cbranch_scc1 .Lx1_generic
	s_load_dwordx2 s[8:9], s[36:37], 0x18
	s_load_dwordx2 s[10:11], s[36:37], 0x78
	v_and_b32_e32 v25, 63, v208
	v_lshrrev_b32_e32 v24, 6, v208
	v_lshlrev_b32_e32 v28, 5, v25
	v_lshlrev_b32_e32 v26, 4, v25
	v_and_b32_e32 v25, 15, v25
	v_lshlrev_b32_e32 v27, 17, v25
	v_readfirstlane_b32 s1, v24
	s_lshl_b32 s3, s2, 3
	s_add_i32 s3, s3, s1
	s_lshl_b32 s40, s94, 12
	s_mov_b32 s48, 0xffff0000
	s_waitcnt lgkmcnt(0)
	s_add_u32 s8, s8, s40
	s_addc_u32 s9, s9, 0
	global_load_dwordx4 v[0:3], v28, s[8:9] offset:2048
	global_load_dwordx4 v[4:7], v28, s[8:9] offset:2064
	global_load_dwordx4 v[8:11], v28, s[8:9]
	global_load_dwordx4 v[12:15], v28, s[8:9] offset:16
	s_mov_b32 s41, 0
	s_mov_b32 s44, s3
	s_mov_b32 s45, 0
	s_lshl_b64 s[46:47], s[44:45], 11
	s_lshl_b64 s[44:45], s[44:45], 2
	s_add_u32 s8, s10, s46
	s_addc_u32 s9, s11, s47
	s_add_u32 s6, s90, 0x4700000
	s_addc_u32 s7, s91, 0
	s_add_u32 s6, s6, s46
	s_addc_u32 s7, s7, s47
	s_add_u32 s10, s90, 0x8d08000
	s_addc_u32 s11, s91, 0
	s_add_u32 s10, s10, s46
	s_addc_u32 s11, s11, s47
	s_add_u32 s12, s90, 0x8900000
	s_addc_u32 s13, s91, 0
	s_add_u32 s12, s12, s44
	s_addc_u32 s13, s13, s45
	s_add_u32 s42, s12, 0x0
	s_addc_u32 s43, s13, 0
	global_load_dword v160, v27, s[42:43]
	s_add_u32 s14, s6, 0x0
	s_addc_u32 s15, s7, 0
	global_load_dwordx4 v[32:35], v26, s[14:15] nt
	global_load_dwordx4 v[40:43], v26, s[14:15] offset:1024 nt
	s_add_u32 s40, s8, 0x0
	s_addc_u32 s41, s9, 0
	global_load_dwordx4 v[36:39], v26, s[40:41] nt
	global_load_dwordx4 v[44:47], v26, s[40:41] offset:1024 nt
	s_add_u32 s42, s12, 0x2000
	s_addc_u32 s43, s13, 0
	global_load_dword v161, v27, s[42:43]
	s_add_u32 s14, s6, 0x400000
	s_addc_u32 s15, s7, 0
	global_load_dwordx4 v[48:51], v26, s[14:15] nt
	global_load_dwordx4 v[56:59], v26, s[14:15] offset:1024 nt
	s_add_u32 s40, s8, 0x400000
	s_addc_u32 s41, s9, 0
	global_load_dwordx4 v[52:55], v26, s[40:41] nt
	global_load_dwordx4 v[60:63], v26, s[40:41] offset:1024 nt
	s_add_u32 s42, s12, 0x4000
	s_addc_u32 s43, s13, 0
	global_load_dword v162, v27, s[42:43]
	s_add_u32 s14, s6, 0x800000
	s_addc_u32 s15, s7, 0
	global_load_dwordx4 v[64:67], v26, s[14:15] nt
	global_load_dwordx4 v[72:75], v26, s[14:15] offset:1024 nt
	s_add_u32 s40, s8, 0x800000
	s_addc_u32 s41, s9, 0
	global_load_dwordx4 v[68:71], v26, s[40:41] nt
	global_load_dwordx4 v[76:79], v26, s[40:41] offset:1024 nt
	s_add_u32 s42, s12, 0x6000
	s_addc_u32 s43, s13, 0
	global_load_dword v163, v27, s[42:43]
	s_add_u32 s14, s6, 0xc00000
	s_addc_u32 s15, s7, 0
	global_load_dwordx4 v[80:83], v26, s[14:15] nt
	global_load_dwordx4 v[88:91], v26, s[14:15] offset:1024 nt
	s_add_u32 s40, s8, 0xc00000
	s_addc_u32 s41, s9, 0
	global_load_dwordx4 v[84:87], v26, s[40:41] nt
	global_load_dwordx4 v[92:95], v26, s[40:41] offset:1024 nt
	s_add_u32 s42, s12, 0x8000
	s_addc_u32 s43, s13, 0
	global_load_dword v164, v27, s[42:43]
	s_add_u32 s14, s6, 0x1000000
	s_addc_u32 s15, s7, 0
	global_load_dwordx4 v[96:99], v26, s[14:15] nt
	global_load_dwordx4 v[104:107], v26, s[14:15] offset:1024 nt
	s_add_u32 s40, s8, 0x1000000
	s_addc_u32 s41, s9, 0
	global_load_dwordx4 v[100:103], v26, s[40:41] nt
	global_load_dwordx4 v[108:111], v26, s[40:41] offset:1024 nt
	s_add_u32 s42, s12, 0xa000
	s_addc_u32 s43, s13, 0
	global_load_dword v165, v27, s[42:43]
	s_add_u32 s14, s6, 0x1400000
	s_addc_u32 s15, s7, 0
	global_load_dwordx4 v[112:115], v26, s[14:15] nt
	global_load_dwordx4 v[120:123], v26, s[14:15] offset:1024 nt
	s_add_u32 s40, s8, 0x1400000
	s_addc_u32 s41, s9, 0
	global_load_dwordx4 v[116:119], v26, s[40:41] nt
	global_load_dwordx4 v[124:127], v26, s[40:41] offset:1024 nt
	s_add_u32 s42, s12, 0xc000
	s_addc_u32 s43, s13, 0
	global_load_dword v166, v27, s[42:43]
	s_add_u32 s14, s6, 0x1800000
	s_addc_u32 s15, s7, 0
	global_load_dwordx4 v[128:131], v26, s[14:15] nt
	global_load_dwordx4 v[136:139], v26, s[14:15] offset:1024 nt
	s_add_u32 s40, s8, 0x1800000
	s_addc_u32 s41, s9, 0
	global_load_dwordx4 v[132:135], v26, s[40:41] nt
	global_load_dwordx4 v[140:143], v26, s[40:41] offset:1024 nt
	s_add_u32 s42, s12, 0xe000
	s_addc_u32 s43, s13, 0
	global_load_dword v167, v27, s[42:43]
	s_add_u32 s14, s6, 0x1c00000
	s_addc_u32 s15, s7, 0
	global_load_dwordx4 v[144:147], v26, s[14:15] nt
	global_load_dwordx4 v[152:155], v26, s[14:15] offset:1024 nt
	s_add_u32 s40, s8, 0x1c00000
	s_addc_u32 s41, s9, 0
	global_load_dwordx4 v[148:151], v26, s[40:41] nt
	global_load_dwordx4 v[156:159], v26, s[40:41] offset:1024 nt
	s_waitcnt vmcnt(35)
; __device__ void phase_x1(KP P, int layer) {
;     ...
;     for (int row = gw; row < MTOK; row += nw) {
;         const float rstd = rsqrtf(ssq2[row] * (1.f / 1024.f) + EPS);
;         if (lane == 0) ssq[row] = 0.f;
; #pragma unroll
;         for (int i = 0; i < 2; ++i) { const size_t off = (size_t)row * 1024 + lane * 8 + 512 * i;
;             float xv[8], mv[8]; unpack8(__builtin_nontemporal_load((const u32x4*)(xin + off)), xv); unpack8(__builtin_nontemporal_load((const u32x4*)(mix + off)), mv);
; #pragma unroll
;             for (int j = 0; j < 4; ++j) { xv[j] += mv[j] * rstd * wv[i][0][j]; xv[4 + j] += mv[4 + j] * rstd * wv[i][1][j]; }
;             *(u32x4*)(x1b + off) = __builtin_bit_cast(u32x4, pack8(xv)); }
	v_add_f32_dpp v160, v160, v160 row_ror:8 row_mask:0xf bank_mask:0xf
	s_nop 1
	v_add_f32_dpp v160, v160, v160 row_ror:4 row_mask:0xf bank_mask:0xf
	s_nop 1
	v_add_f32_dpp v160, v160, v160 row_ror:2 row_mask:0xf bank_mask:0xf
	s_nop 1
	v_add_f32_dpp v160, v160, v160 row_ror:1 row_mask:0xf bank_mask:0xf
	s_nop 1
	v_readfirstlane_b32 s44, v160
	s_add_u32 s46, s10, 0x0
	s_addc_u32 s47, s11, 0
	v_mov_b32_e32 v25, s44
	v_fmamk_f32 v25, v25, 0x3a800000, v209
	v_rsq_f32_e32 v24, v25
	s_nop 0
	v_lshlrev_b32_e32 v16, 16, v36
	v_and_b32_e32 v36, s48, v36
	v_lshlrev_b32_e32 v17, 16, v32
	v_and_b32_e32 v32, s48, v32
	v_lshlrev_b32_e32 v18, 16, v37
	v_and_b32_e32 v37, s48, v37
	v_lshlrev_b32_e32 v19, 16, v33
	v_and_b32_e32 v33, s48, v33
	v_lshlrev_b32_e32 v20, 16, v38
	v_and_b32_e32 v38, s48, v38
	v_lshlrev_b32_e32 v21, 16, v34
	v_and_b32_e32 v34, s48, v34
	v_lshlrev_b32_e32 v22, 16, v39
	v_and_b32_e32 v39, s48, v39
	v_lshlrev_b32_e32 v23, 16, v35
	v_and_b32_e32 v35, s48, v35
	v_mul_f32_e32 v16, v24, v16
	v_mul_f32_e32 v36, v24, v36
	v_mul_f32_e32 v18, v24, v18
	v_mul_f32_e32 v37, v24, v37
	v_mul_f32_e32 v20, v24, v20
	v_mul_f32_e32 v38, v24, v38
	v_mul_f32_e32 v22, v24, v22
	v_mul_f32_e32 v39, v24, v39
	v_fmac_f32_e32 v17, v8, v16
	v_fmac_f32_e32 v32, v9, v36
	v_fmac_f32_e32 v19, v10, v18
	v_fmac_f32_e32 v33, v11, v37
	v_fmac_f32_e32 v21, v12, v20
	v_fmac_f32_e32 v34, v13, v38
	v_fmac_f32_e32 v23, v14, v22
	v_fmac_f32_e32 v35, v15, v39
	v_cvt_pk_bf16_f32 v32, v17, v32
	v_cvt_pk_bf16_f32 v33, v19, v33
	v_cvt_pk_bf16_f32 v34, v21, v34
	v_cvt_pk_bf16_f32 v35, v23, v35
	global_store_dwordx4 v26, v[32:35], s[46:47]
	v_lshlrev_b32_e32 v16, 16, v44
	v_and_b32_e32 v44, s48, v44
	v_lshlrev_b32_e32 v17, 16, v40
	v_and_b32_e32 v40, s48, v40
	v_lshlrev_b32_e32 v18, 16, v45
	v_and_b32_e32 v45, s48, v45
	v_lshlrev_b32_e32 v19, 16, v41
	v_and_b32_e32 v41, s48, v41
	v_lshlrev_b32_e32 v20, 16, v46
	v_and_b32_e32 v46, s48, v46
	v_lshlrev_b32_e32 v21, 16, v42
	v_and_b32_e32 v42, s48, v42
	v_lshlrev_b32_e32 v22, 16, v47
	v_and_b32_e32 v47, s48, v47
	v_lshlrev_b32_e32 v23, 16, v43
	v_and_b32_e32 v43, s48, v43
	v_mul_f32_e32 v16, v24, v16
	v_mul_f32_e32 v44, v24, v44
	v_mul_f32_e32 v18, v24, v18
	v_mul_f32_e32 v45, v24, v45
	v_mul_f32_e32 v20, v24, v20
	v_mul_f32_e32 v46, v24, v46
	v_mul_f32_e32 v22, v24, v22
	v_mul_f32_e32 v47, v24, v47
	v_fmac_f32_e32 v17, v0, v16
	v_fmac_f32_e32 v40, v1, v44
	v_fmac_f32_e32 v19, v2, v18
	v_fmac_f32_e32 v41, v3, v45
	v_fmac_f32_e32 v21, v4, v20
	v_fmac_f32_e32 v42, v5, v46
	v_fmac_f32_e32 v23, v6, v22
	v_fmac_f32_e32 v43, v7, v47
	v_cvt_pk_bf16_f32 v40, v17, v40
	v_cvt_pk_bf16_f32 v41, v19, v41
	v_cvt_pk_bf16_f32 v42, v21, v42
	v_cvt_pk_bf16_f32 v43, v23, v43
	global_store_dwordx4 v26, v[40:43], s[46:47] offset:1024
	s_add_u32 s42, s12, 0x10000
	s_addc_u32 s43, s13, 0
	global_load_dword v160, v27, s[42:43]
	s_add_u32 s14, s6, 0x2000000
	s_addc_u32 s15, s7, 0
	global_load_dwordx4 v[32:35], v26, s[14:15] nt
	global_load_dwordx4 v[40:43], v26, s[14:15] offset:1024 nt
	s_add_u32 s40, s8, 0x2000000
	s_addc_u32 s41, s9, 0
	global_load_dwordx4 v[36:39], v26, s[40:41] nt
	global_load_dwordx4 v[44:47], v26, s[40:41] offset:1024 nt
	s_waitcnt vmcnt(37)
	v_add_f32_dpp v161, v161, v161 row_ror:8 row_mask:0xf bank_mask:0xf
	s_nop 1
	v_add_f32_dpp v161, v161, v161 row_ror:4 row_mask:0xf bank_mask:0xf
	s_nop 1
	v_add_f32_dpp v161, v161, v161 row_ror:2 row_mask:0xf bank_mask:0xf
	s_nop 1
	v_add_f32_dpp v161, v161, v161 row_ror:1 row_mask:0xf bank_mask:0xf
	s_nop 1
	v_readfirstlane_b32 s44, v161
	s_add_u32 s46, s10, 0x400000
	s_addc_u32 s47, s11, 0
	v_mov_b32_e32 v25, s44
	v_fmamk_f32 v25, v25, 0x3a800000, v209
	v_rsq_f32_e32 v24, v25
	s_nop 0
	v_lshlrev_b32_e32 v16, 16, v52
	v_and_b32_e32 v52, s48, v52
	v_lshlrev_b32_e32 v17, 16, v48
	v_and_b32_e32 v48, s48, v48
	v_lshlrev_b32_e32 v18, 16, v53
	v_and_b32_e32 v53, s48, v53
	v_lshlrev_b32_e32 v19, 16, v49
	v_and_b32_e32 v49, s48, v49
	v_lshlrev_b32_e32 v20, 16, v54
	v_and_b32_e32 v54, s48, v54
	v_lshlrev_b32_e32 v21, 16, v50
	v_and_b32_e32 v50, s48, v50
	v_lshlrev_b32_e32 v22, 16, v55
	v_and_b32_e32 v55, s48, v55
	v_lshlrev_b32_e32 v23, 16, v51
	v_and_b32_e32 v51, s48, v51
	v_mul_f32_e32 v16, v24, v16
	v_mul_f32_e32 v52, v24, v52
	v_mul_f32_e32 v18, v24, v18
	v_mul_f32_e32 v53, v24, v53
	v_mul_f32_e32 v20, v24, v20
	v_mul_f32_e32 v54, v24, v54
	v_mul_f32_e32 v22, v24, v22
	v_mul_f32_e32 v55, v24, v55
	v_fmac_f32_e32 v17, v8, v16
	v_fmac_f32_e32 v48, v9, v52
	v_fmac_f32_e32 v19, v10, v18
	v_fmac_f32_e32 v49, v11, v53
	v_fmac_f32_e32 v21, v12, v20
	v_fmac_f32_e32 v50, v13, v54
	v_fmac_f32_e32 v23, v14, v22
	v_fmac_f32_e32 v51, v15, v55
	v_cvt_pk_bf16_f32 v48, v17, v48
	v_cvt_pk_bf16_f32 v49, v19, v49
	v_cvt_pk_bf16_f32 v50, v21, v50
	v_cvt_pk_bf16_f32 v51, v23, v51
	global_store_dwordx4 v26, v[48:51], s[46:47]
	v_lshlrev_b32_e32 v16, 16, v60
	v_and_b32_e32 v60, s48, v60
	v_lshlrev_b32_e32 v17, 16, v56
	v_and_b32_e32 v56, s48, v56
	v_lshlrev_b32_e32 v18, 16, v61
	v_and_b32_e32 v61, s48, v61
	v_lshlrev_b32_e32 v19, 16, v57
	v_and_b32_e32 v57, s48, v57
	v_lshlrev_b32_e32 v20, 16, v62
	v_and_b32_e32 v62, s48, v62
	v_lshlrev_b32_e32 v21, 16, v58
	v_and_b32_e32 v58, s48, v58
	v_lshlrev_b32_e32 v22, 16, v63
	v_and_b32_e32 v63, s48, v63
	v_lshlrev_b32_e32 v23, 16, v59
	v_and_b32_e32 v59, s48, v59
	v_mul_f32_e32 v16, v24, v16
	v_mul_f32_e32 v60, v24, v60
	v_mul_f32_e32 v18, v24, v18
	v_mul_f32_e32 v61, v24, v61
	v_mul_f32_e32 v20, v24, v20
	v_mul_f32_e32 v62, v24, v62
	v_mul_f32_e32 v22, v24, v22
	v_mul_f32_e32 v63, v24, v63
	v_fmac_f32_e32 v17, v0, v16
	v_fmac_f32_e32 v56, v1, v60
	v_fmac_f32_e32 v19, v2, v18
	v_fmac_f32_e32 v57, v3, v61
	v_fmac_f32_e32 v21, v4, v20
	v_fmac_f32_e32 v58, v5, v62
	v_fmac_f32_e32 v23, v6, v22
	v_fmac_f32_e32 v59, v7, v63
	v_cvt_pk_bf16_f32 v56, v17, v56
	v_cvt_pk_bf16_f32 v57, v19, v57
	v_cvt_pk_bf16_f32 v58, v21, v58
	v_cvt_pk_bf16_f32 v59, v23, v59
	global_store_dwordx4 v26, v[56:59], s[46:47] offset:1024
	s_add_u32 s42, s12, 0x12000
	s_addc_u32 s43, s13, 0
	global_load_dword v161, v27, s[42:43]
	s_add_u32 s14, s6, 0x2400000
	s_addc_u32 s15, s7, 0
	global_load_dwordx4 v[48:51], v26, s[14:15] nt
	global_load_dwordx4 v[56:59], v26, s[14:15] offset:1024 nt
	s_add_u32 s40, s8, 0x2400000
	s_addc_u32 s41, s9, 0
	global_load_dwordx4 v[52:55], v26, s[40:41] nt
	global_load_dwordx4 v[60:63], v26, s[40:41] offset:1024 nt
	s_waitcnt vmcnt(39)
; __device__ void phase_x1(KP P, int layer) {
;     ...
;     for (int row = gw; row < MTOK; row += nw) {
;         const float rstd = rsqrtf(ssq2[row] * (1.f / 1024.f) + EPS);
;         if (lane == 0) ssq[row] = 0.f;
; #pragma unroll
;         for (int i = 0; i < 2; ++i) { const size_t off = (size_t)row * 1024 + lane * 8 + 512 * i;
;             float xv[8], mv[8]; unpack8(__builtin_nontemporal_load((const u32x4*)(xin + off)), xv); unpack8(__builtin_nontemporal_load((const u32x4*)(mix + off)), mv);
; #pragma unroll
;             for (int j = 0; j < 4; ++j) { xv[j] += mv[j] * rstd * wv[i][0][j]; xv[4 + j] += mv[4 + j] * rstd * wv[i][1][j]; }
;             *(u32x4*)(x1b + off) = __builtin_bit_cast(u32x4, pack8(xv)); }
	v_add_f32_dpp v162, v162, v162 row_ror:8 row_mask:0xf bank_mask:0xf
	s_nop 1
	v_add_f32_dpp v162, v162, v162 row_ror:4 row_mask:0xf bank_mask:0xf
	s_nop 1
	v_add_f32_dpp v162, v162, v162 row_ror:2 row_mask:0xf bank_mask:0xf
	s_nop 1
	v_add_f32_dpp v162, v162, v162 row_ror:1 row_mask:0xf bank_mask:0xf
	s_nop 1
	v_readfirstlane_b32 s44, v162
	s_add_u32 s46, s10, 0x800000
	s_addc_u32 s47, s11, 0
	v_mov_b32_e32 v25, s44
	v_fmamk_f32 v25, v25, 0x3a800000, v209
	v_rsq_f32_e32 v24, v25
	s_nop 0
	v_lshlrev_b32_e32 v16, 16, v68
	v_and_b32_e32 v68, s48, v68
	v_lshlrev_b32_e32 v17, 16, v64
	v_and_b32_e32 v64, s48, v64
	v_lshlrev_b32_e32 v18, 16, v69
	v_and_b32_e32 v69, s48, v69
	v_lshlrev_b32_e32 v19, 16, v65
	v_and_b32_e32 v65, s48, v65
	v_lshlrev_b32_e32 v20, 16, v70
	v_and_b32_e32 v70, s48, v70
	v_lshlrev_b32_e32 v21, 16, v66
	v_and_b32_e32 v66, s48, v66
	v_lshlrev_b32_e32 v22, 16, v71
	v_and_b32_e32 v71, s48, v71
	v_lshlrev_b32_e32 v23, 16, v67
	v_and_b32_e32 v67, s48, v67
	v_mul_f32_e32 v16, v24, v16
	v_mul_f32_e32 v68, v24, v68
	v_mul_f32_e32 v18, v24, v18
	v_mul_f32_e32 v69, v24, v69
	v_mul_f32_e32 v20, v24, v20
	v_mul_f32_e32 v70, v24, v70
	v_mul_f32_e32 v22, v24, v22
	v_mul_f32_e32 v71, v24, v71
	v_fmac_f32_e32 v17, v8, v16
	v_fmac_f32_e32 v64, v9, v68
	v_fmac_f32_e32 v19, v10, v18
	v_fmac_f32_e32 v65, v11, v69
	v_fmac_f32_e32 v21, v12, v20
	v_fmac_f32_e32 v66, v13, v70
	v_fmac_f32_e32 v23, v14, v22
	v_fmac_f32_e32 v67, v15, v71
	v_cvt_pk_bf16_f32 v64, v17, v64
	v_cvt_pk_bf16_f32 v65, v19, v65
	v_cvt_pk_bf16_f32 v66, v21, v66
	v_cvt_pk_bf16_f32 v67, v23, v67
	global_store_dwordx4 v26, v[64:67], s[46:47]
	v_lshlrev_b32_e32 v16, 16, v76
	v_and_b32_e32 v76, s48, v76
	v_lshlrev_b32_e32 v17, 16, v72
	v_and_b32_e32 v72, s48, v72
	v_lshlrev_b32_e32 v18, 16, v77
	v_and_b32_e32 v77, s48, v77
	v_lshlrev_b32_e32 v19, 16, v73
	v_and_b32_e32 v73, s48, v73
	v_lshlrev_b32_e32 v20, 16, v78
	v_and_b32_e32 v78, s48, v78
	v_lshlrev_b32_e32 v21, 16, v74
	v_and_b32_e32 v74, s48, v74
	v_lshlrev_b32_e32 v22, 16, v79
	v_and_b32_e32 v79, s48, v79
	v_lshlrev_b32_e32 v23, 16, v75
	v_and_b32_e32 v75, s48, v75
	v_mul_f32_e32 v16, v24, v16
	v_mul_f32_e32 v76, v24, v76
	v_mul_f32_e32 v18, v24, v18
	v_mul_f32_e32 v77, v24, v77
	v_mul_f32_e32 v20, v24, v20
	v_mul_f32_e32 v78, v24, v78
	v_mul_f32_e32 v22, v24, v22
	v_mul_f32_e32 v79, v24, v79
	v_fmac_f32_e32 v17, v0, v16
	v_fmac_f32_e32 v72, v1, v76
	v_fmac_f32_e32 v19, v2, v18
	v_fmac_f32_e32 v73, v3, v77
	v_fmac_f32_e32 v21, v4, v20
	v_fmac_f32_e32 v74, v5, v78
	v_fmac_f32_e32 v23, v6, v22
	v_fmac_f32_e32 v75, v7, v79
	v_cvt_pk_bf16_f32 v72, v17, v72
	v_cvt_pk_bf16_f32 v73, v19, v73
	v_cvt_pk_bf16_f32 v74, v21, v74
	v_cvt_pk_bf16_f32 v75, v23, v75
	global_store_dwordx4 v26, v[72:75], s[46:47] offset:1024
	s_add_u32 s42, s12, 0x14000
	s_addc_u32 s43, s13, 0
	global_load_dword v162, v27, s[42:43]
	s_add_u32 s14, s6, 0x2800000
	s_addc_u32 s15, s7, 0
	global_load_dwordx4 v[64:67], v26, s[14:15] nt
	global_load_dwordx4 v[72:75], v26, s[14:15] offset:1024 nt
	s_add_u32 s40, s8, 0x2800000
	s_addc_u32 s41, s9, 0
	global_load_dwordx4 v[68:71], v26, s[40:41] nt
	global_load_dwordx4 v[76:79], v26, s[40:41] offset:1024 nt
	s_waitcnt vmcnt(41)
	v_add_f32_dpp v163, v163, v163 row_ror:8 row_mask:0xf bank_mask:0xf
	s_nop 1
	v_add_f32_dpp v163, v163, v163 row_ror:4 row_mask:0xf bank_mask:0xf
	s_nop 1
	v_add_f32_dpp v163, v163, v163 row_ror:2 row_mask:0xf bank_mask:0xf
	s_nop 1
	v_add_f32_dpp v163, v163, v163 row_ror:1 row_mask:0xf bank_mask:0xf
	s_nop 1
	v_readfirstlane_b32 s44, v163
	s_add_u32 s46, s10, 0xc00000
	s_addc_u32 s47, s11, 0
	v_mov_b32_e32 v25, s44
	v_fmamk_f32 v25, v25, 0x3a800000, v209
	v_rsq_f32_e32 v24, v25
	s_nop 0
	v_lshlrev_b32_e32 v16, 16, v84
	v_and_b32_e32 v84, s48, v84
	v_lshlrev_b32_e32 v17, 16, v80
	v_and_b32_e32 v80, s48, v80
	v_lshlrev_b32_e32 v18, 16, v85
	v_and_b32_e32 v85, s48, v85
	v_lshlrev_b32_e32 v19, 16, v81
	v_and_b32_e32 v81, s48, v81
	v_lshlrev_b32_e32 v20, 16, v86
	v_and_b32_e32 v86, s48, v86
	v_lshlrev_b32_e32 v21, 16, v82
	v_and_b32_e32 v82, s48, v82
	v_lshlrev_b32_e32 v22, 16, v87
	v_and_b32_e32 v87, s48, v87
	v_lshlrev_b32_e32 v23, 16, v83
	v_and_b32_e32 v83, s48, v83
	v_mul_f32_e32 v16, v24, v16
	v_mul_f32_e32 v84, v24, v84
	v_mul_f32_e32 v18, v24, v18
	v_mul_f32_e32 v85, v24, v85
	v_mul_f32_e32 v20, v24, v20
	v_mul_f32_e32 v86, v24, v86
	v_mul_f32_e32 v22, v24, v22
	v_mul_f32_e32 v87, v24, v87
	v_fmac_f32_e32 v17, v8, v16
	v_fmac_f32_e32 v80, v9, v84
	v_fmac_f32_e32 v19, v10, v18
	v_fmac_f32_e32 v81, v11, v85
	v_fmac_f32_e32 v21, v12, v20
	v_fmac_f32_e32 v82, v13, v86
	v_fmac_f32_e32 v23, v14, v22
	v_fmac_f32_e32 v83, v15, v87
	v_cvt_pk_bf16_f32 v80, v17, v80
	v_cvt_pk_bf16_f32 v81, v19, v81
	v_cvt_pk_bf16_f32 v82, v21, v82
	v_cvt_pk_bf16_f32 v83, v23, v83
	global_store_dwordx4 v26, v[80:83], s[46:47]
	v_lshlrev_b32_e32 v16, 16, v92
	v_and_b32_e32 v92, s48, v92
	v_lshlrev_b32_e32 v17, 16, v88
	v_and_b32_e32 v88, s48, v88
	v_lshlrev_b32_e32 v18, 16, v93
	v_and_b32_e32 v93, s48, v93
	v_lshlrev_b32_e32 v19, 16, v89
	v_and_b32_e32 v89, s48, v89
	v_lshlrev_b32_e32 v20, 16, v94
	v_and_b32_e32 v94, s48, v94
	v_lshlrev_b32_e32 v21, 16, v90
	v_and_b32_e32 v90, s48, v90
	v_lshlrev_b32_e32 v22, 16, v95
	v_and_b32_e32 v95, s48, v95
	v_lshlrev_b32_e32 v23, 16, v91
	v_and_b32_e32 v91, s48, v91
	v_mul_f32_e32 v16, v24, v16
	v_mul_f32_e32 v92, v24, v92
	v_mul_f32_e32 v18, v24, v18
	v_mul_f32_e32 v93, v24, v93
	v_mul_f32_e32 v20, v24, v20
	v_mul_f32_e32 v94, v24, v94
	v_mul_f32_e32 v22, v24, v22
	v_mul_f32_e32 v95, v24, v95
	v_fmac_f32_e32 v17, v0, v16
	v_fmac_f32_e32 v88, v1, v92
	v_fmac_f32_e32 v19, v2, v18
	v_fmac_f32_e32 v89, v3, v93
	v_fmac_f32_e32 v21, v4, v20
	v_fmac_f32_e32 v90, v5, v94
	v_fmac_f32_e32 v23, v6, v22
	v_fmac_f32_e32 v91, v7, v95
	v_cvt_pk_bf16_f32 v88, v17, v88
	v_cvt_pk_bf16_f32 v89, v19, v89
	v_cvt_pk_bf16_f32 v90, v21, v90
	v_cvt_pk_bf16_f32 v91, v23, v91
	global_store_dwordx4 v26, v[88:91], s[46:47] offset:1024
	s_add_u32 s42, s12, 0x16000
	s_addc_u32 s43, s13, 0
	global_load_dword v163, v27, s[42:43]
	s_add_u32 s14, s6, 0x2c00000
	s_addc_u32 s15, s7, 0
	global_load_dwordx4 v[80:83], v26, s[14:15] nt
	global_load_dwordx4 v[88:91], v26, s[14:15] offset:1024 nt
	s_add_u32 s40, s8, 0x2c00000
	s_addc_u32 s41, s9, 0
	global_load_dwordx4 v[84:87], v26, s[40:41] nt
	global_load_dwordx4 v[92:95], v26, s[40:41] offset:1024 nt
	s_waitcnt vmcnt(43)
; __device__ void phase_x1(KP P, int layer) {
;     ...
;     for (int row = gw; row < MTOK; row += nw) {
;         const float rstd = rsqrtf(ssq2[row] * (1.f / 1024.f) + EPS);
;         if (lane == 0) ssq[row] = 0.f;
; #pragma unroll
;         for (int i = 0; i < 2; ++i) { const size_t off = (size_t)row * 1024 + lane * 8 + 512 * i;
;             float xv[8], mv[8]; unpack8(__builtin_nontemporal_load((const u32x4*)(xin + off)), xv); unpack8(__builtin_nontemporal_load((const u32x4*)(mix + off)), mv);
; #pragma unroll
;             for (int j = 0; j < 4; ++j) { xv[j] += mv[j] * rstd * wv[i][0][j]; xv[4 + j] += mv[4 + j] * rstd * wv[i][1][j]; }
;             *(u32x4*)(x1b + off) = __builtin_bit_cast(u32x4, pack8(xv)); }
	v_add_f32_dpp v164, v164, v164 row_ror:8 row_mask:0xf bank_mask:0xf
	s_nop 1
	v_add_f32_dpp v164, v164, v164 row_ror:4 row_mask:0xf bank_mask:0xf
	s_nop 1
	v_add_f32_dpp v164, v164, v164 row_ror:2 row_mask:0xf bank_mask:0xf
	s_nop 1
	v_add_f32_dpp v164, v164, v164 row_ror:1 row_mask:0xf bank_mask:0xf
	s_nop 1
	v_readfirstlane_b32 s44, v164
	s_add_u32 s46, s10, 0x1000000
	s_addc_u32 s47, s11, 0
	v_mov_b32_e32 v25, s44
	v_fmamk_f32 v25, v25, 0x3a800000, v209
	v_rsq_f32_e32 v24, v25
	s_nop 0
	v_lshlrev_b32_e32 v16, 16, v100
	v_and_b32_e32 v100, s48, v100
	v_lshlrev_b32_e32 v17, 16, v96
	v_and_b32_e32 v96, s48, v96
	v_lshlrev_b32_e32 v18, 16, v101
	v_and_b32_e32 v101, s48, v101
	v_lshlrev_b32_e32 v19, 16, v97
	v_and_b32_e32 v97, s48, v97
	v_lshlrev_b32_e32 v20, 16, v102
	v_and_b32_e32 v102, s48, v102
	v_lshlrev_b32_e32 v21, 16, v98
	v_and_b32_e32 v98, s48, v98
	v_lshlrev_b32_e32 v22, 16, v103
	v_and_b32_e32 v103, s48, v103
	v_lshlrev_b32_e32 v23, 16, v99
	v_and_b32_e32 v99, s48, v99
	v_mul_f32_e32 v16, v24, v16
	v_mul_f32_e32 v100, v24, v100
	v_mul_f32_e32 v18, v24, v18
	v_mul_f32_e32 v101, v24, v101
	v_mul_f32_e32 v20, v24, v20
	v_mul_f32_e32 v102, v24, v102
	v_mul_f32_e32 v22, v24, v22
	v_mul_f32_e32 v103, v24, v103
	v_fmac_f32_e32 v17, v8, v16
	v_fmac_f32_e32 v96, v9, v100
	v_fmac_f32_e32 v19, v10, v18
	v_fmac_f32_e32 v97, v11, v101
	v_fmac_f32_e32 v21, v12, v20
	v_fmac_f32_e32 v98, v13, v102
	v_fmac_f32_e32 v23, v14, v22
	v_fmac_f32_e32 v99, v15, v103
	v_cvt_pk_bf16_f32 v96, v17, v96
	v_cvt_pk_bf16_f32 v97, v19, v97
	v_cvt_pk_bf16_f32 v98, v21, v98
	v_cvt_pk_bf16_f32 v99, v23, v99
	global_store_dwordx4 v26, v[96:99], s[46:47]
	v_lshlrev_b32_e32 v16, 16, v108
	v_and_b32_e32 v108, s48, v108
	v_lshlrev_b32_e32 v17, 16, v104
	v_and_b32_e32 v104, s48, v104
	v_lshlrev_b32_e32 v18, 16, v109
	v_and_b32_e32 v109, s48, v109
	v_lshlrev_b32_e32 v19, 16, v105
	v_and_b32_e32 v105, s48, v105
	v_lshlrev_b32_e32 v20, 16, v110
	v_and_b32_e32 v110, s48, v110
	v_lshlrev_b32_e32 v21, 16, v106
	v_and_b32_e32 v106, s48, v106
	v_lshlrev_b32_e32 v22, 16, v111
	v_and_b32_e32 v111, s48, v111
	v_lshlrev_b32_e32 v23, 16, v107
	v_and_b32_e32 v107, s48, v107
	v_mul_f32_e32 v16, v24, v16
	v_mul_f32_e32 v108, v24, v108
	v_mul_f32_e32 v18, v24, v18
	v_mul_f32_e32 v109, v24, v109
	v_mul_f32_e32 v20, v24, v20
	v_mul_f32_e32 v110, v24, v110
	v_mul_f32_e32 v22, v24, v22
	v_mul_f32_e32 v111, v24, v111
	v_fmac_f32_e32 v17, v0, v16
	v_fmac_f32_e32 v104, v1, v108
	v_fmac_f32_e32 v19, v2, v18
	v_fmac_f32_e32 v105, v3, v109
	v_fmac_f32_e32 v21, v4, v20
	v_fmac_f32_e32 v106, v5, v110
	v_fmac_f32_e32 v23, v6, v22
	v_fmac_f32_e32 v107, v7, v111
	v_cvt_pk_bf16_f32 v104, v17, v104
	v_cvt_pk_bf16_f32 v105, v19, v105
	v_cvt_pk_bf16_f32 v106, v21, v106
	v_cvt_pk_bf16_f32 v107, v23, v107
	global_store_dwordx4 v26, v[104:107], s[46:47] offset:1024
	s_add_u32 s42, s12, 0x18000
	s_addc_u32 s43, s13, 0
	global_load_dword v164, v27, s[42:43]
	s_add_u32 s14, s6, 0x3000000
	s_addc_u32 s15, s7, 0
	global_load_dwordx4 v[96:99], v26, s[14:15] nt
	global_load_dwordx4 v[104:107], v26, s[14:15] offset:1024 nt
	s_add_u32 s40, s8, 0x3000000
	s_addc_u32 s41, s9, 0
	global_load_dwordx4 v[100:103], v26, s[40:41] nt
	global_load_dwordx4 v[108:111], v26, s[40:41] offset:1024 nt
	s_waitcnt vmcnt(45)
	v_add_f32_dpp v165, v165, v165 row_ror:8 row_mask:0xf bank_mask:0xf
	s_nop 1
	v_add_f32_dpp v165, v165, v165 row_ror:4 row_mask:0xf bank_mask:0xf
	s_nop 1
	v_add_f32_dpp v165, v165, v165 row_ror:2 row_mask:0xf bank_mask:0xf
	s_nop 1
	v_add_f32_dpp v165, v165, v165 row_ror:1 row_mask:0xf bank_mask:0xf
	s_nop 1
	v_readfirstlane_b32 s44, v165
	s_add_u32 s46, s10, 0x1400000
	s_addc_u32 s47, s11, 0
	v_mov_b32_e32 v25, s44
	v_fmamk_f32 v25, v25, 0x3a800000, v209
	v_rsq_f32_e32 v24, v25
	s_nop 0
	v_lshlrev_b32_e32 v16, 16, v116
	v_and_b32_e32 v116, s48, v116
	v_lshlrev_b32_e32 v17, 16, v112
	v_and_b32_e32 v112, s48, v112
	v_lshlrev_b32_e32 v18, 16, v117
	v_and_b32_e32 v117, s48, v117
	v_lshlrev_b32_e32 v19, 16, v113
	v_and_b32_e32 v113, s48, v113
	v_lshlrev_b32_e32 v20, 16, v118
	v_and_b32_e32 v118, s48, v118
	v_lshlrev_b32_e32 v21, 16, v114
	v_and_b32_e32 v114, s48, v114
	v_lshlrev_b32_e32 v22, 16, v119
	v_and_b32_e32 v119, s48, v119
	v_lshlrev_b32_e32 v23, 16, v115
	v_and_b32_e32 v115, s48, v115
	v_mul_f32_e32 v16, v24, v16
	v_mul_f32_e32 v116, v24, v116
	v_mul_f32_e32 v18, v24, v18
	v_mul_f32_e32 v117, v24, v117
	v_mul_f32_e32 v20, v24, v20
	v_mul_f32_e32 v118, v24, v118
	v_mul_f32_e32 v22, v24, v22
	v_mul_f32_e32 v119, v24, v119
	v_fmac_f32_e32 v17, v8, v16
	v_fmac_f32_e32 v112, v9, v116
	v_fmac_f32_e32 v19, v10, v18
	v_fmac_f32_e32 v113, v11, v117
	v_fmac_f32_e32 v21, v12, v20
	v_fmac_f32_e32 v114, v13, v118
	v_fmac_f32_e32 v23, v14, v22
	v_fmac_f32_e32 v115, v15, v119
	v_cvt_pk_bf16_f32 v112, v17, v112
	v_cvt_pk_bf16_f32 v113, v19, v113
	v_cvt_pk_bf16_f32 v114, v21, v114
	v_cvt_pk_bf16_f32 v115, v23, v115
	global_store_dwordx4 v26, v[112:115], s[46:47]
	v_lshlrev_b32_e32 v16, 16, v124
	v_and_b32_e32 v124, s48, v124
	v_lshlrev_b32_e32 v17, 16, v120
	v_and_b32_e32 v120, s48, v120
	v_lshlrev_b32_e32 v18, 16, v125
	v_and_b32_e32 v125, s48, v125
	v_lshlrev_b32_e32 v19, 16, v121
	v_and_b32_e32 v121, s48, v121
	v_lshlrev_b32_e32 v20, 16, v126
	v_and_b32_e32 v126, s48, v126
	v_lshlrev_b32_e32 v21, 16, v122
	v_and_b32_e32 v122, s48, v122
	v_lshlrev_b32_e32 v22, 16, v127
	v_and_b32_e32 v127, s48, v127
	v_lshlrev_b32_e32 v23, 16, v123
	v_and_b32_e32 v123, s48, v123
	v_mul_f32_e32 v16, v24, v16
	v_mul_f32_e32 v124, v24, v124
	v_mul_f32_e32 v18, v24, v18
	v_mul_f32_e32 v125, v24, v125
	v_mul_f32_e32 v20, v24, v20
	v_mul_f32_e32 v126, v24, v126
	v_mul_f32_e32 v22, v24, v22
	v_mul_f32_e32 v127, v24, v127
	v_fmac_f32_e32 v17, v0, v16
	v_fmac_f32_e32 v120, v1, v124
	v_fmac_f32_e32 v19, v2, v18
	v_fmac_f32_e32 v121, v3, v125
	v_fmac_f32_e32 v21, v4, v20
	v_fmac_f32_e32 v122, v5, v126
	v_fmac_f32_e32 v23, v6, v22
	v_fmac_f32_e32 v123, v7, v127
	v_cvt_pk_bf16_f32 v120, v17, v120
	v_cvt_pk_bf16_f32 v121, v19, v121
	v_cvt_pk_bf16_f32 v122, v21, v122
	v_cvt_pk_bf16_f32 v123, v23, v123
	global_store_dwordx4 v26, v[120:123], s[46:47] offset:1024
	s_add_u32 s42, s12, 0x1a000
	s_addc_u32 s43, s13, 0
	global_load_dword v165, v27, s[42:43]
	s_add_u32 s14, s6, 0x3400000
	s_addc_u32 s15, s7, 0
	global_load_dwordx4 v[112:115], v26, s[14:15] nt
	global_load_dwordx4 v[120:123], v26, s[14:15] offset:1024 nt
	s_add_u32 s40, s8, 0x3400000
	s_addc_u32 s41, s9, 0
	global_load_dwordx4 v[116:119], v26, s[40:41] nt
	global_load_dwordx4 v[124:127], v26, s[40:41] offset:1024 nt
	s_waitcnt vmcnt(47)
; __device__ void phase_x1(KP P, int layer) {
;     ...
;     for (int row = gw; row < MTOK; row += nw) {
;         const float rstd = rsqrtf(ssq2[row] * (1.f / 1024.f) + EPS);
;         if (lane == 0) ssq[row] = 0.f;
; #pragma unroll
;         for (int i = 0; i < 2; ++i) { const size_t off = (size_t)row * 1024 + lane * 8 + 512 * i;
;             float xv[8], mv[8]; unpack8(__builtin_nontemporal_load((const u32x4*)(xin + off)), xv); unpack8(__builtin_nontemporal_load((const u32x4*)(mix + off)), mv);
; #pragma unroll
;             for (int j = 0; j < 4; ++j) { xv[j] += mv[j] * rstd * wv[i][0][j]; xv[4 + j] += mv[4 + j] * rstd * wv[i][1][j]; }
;             *(u32x4*)(x1b + off) = __builtin_bit_cast(u32x4, pack8(xv)); }
	v_add_f32_dpp v166, v166, v166 row_ror:8 row_mask:0xf bank_mask:0xf
	s_nop 1
	v_add_f32_dpp v166, v166, v166 row_ror:4 row_mask:0xf bank_mask:0xf
	s_nop 1
	v_add_f32_dpp v166, v166, v166 row_ror:2 row_mask:0xf bank_mask:0xf
	s_nop 1
	v_add_f32_dpp v166, v166, v166 row_ror:1 row_mask:0xf bank_mask:0xf
	s_nop 1
	v_readfirstlane_b32 s44, v166
	s_add_u32 s46, s10, 0x1800000
	s_addc_u32 s47, s11, 0
	v_mov_b32_e32 v25, s44
	v_fmamk_f32 v25, v25, 0x3a800000, v209
	v_rsq_f32_e32 v24, v25
	s_nop 0
	v_lshlrev_b32_e32 v16, 16, v132
	v_and_b32_e32 v132, s48, v132
	v_lshlrev_b32_e32 v17, 16, v128
	v_and_b32_e32 v128, s48, v128
	v_lshlrev_b32_e32 v18, 16, v133
	v_and_b32_e32 v133, s48, v133
	v_lshlrev_b32_e32 v19, 16, v129
	v_and_b32_e32 v129, s48, v129
	v_lshlrev_b32_e32 v20, 16, v134
	v_and_b32_e32 v134, s48, v134
	v_lshlrev_b32_e32 v21, 16, v130
	v_and_b32_e32 v130, s48, v130
	v_lshlrev_b32_e32 v22, 16, v135
	v_and_b32_e32 v135, s48, v135
	v_lshlrev_b32_e32 v23, 16, v131
	v_and_b32_e32 v131, s48, v131
	v_mul_f32_e32 v16, v24, v16
	v_mul_f32_e32 v132, v24, v132
	v_mul_f32_e32 v18, v24, v18
	v_mul_f32_e32 v133, v24, v133
	v_mul_f32_e32 v20, v24, v20
	v_mul_f32_e32 v134, v24, v134
	v_mul_f32_e32 v22, v24, v22
	v_mul_f32_e32 v135, v24, v135
	v_fmac_f32_e32 v17, v8, v16
	v_fmac_f32_e32 v128, v9, v132
	v_fmac_f32_e32 v19, v10, v18
	v_fmac_f32_e32 v129, v11, v133
	v_fmac_f32_e32 v21, v12, v20
	v_fmac_f32_e32 v130, v13, v134
	v_fmac_f32_e32 v23, v14, v22
	v_fmac_f32_e32 v131, v15, v135
	v_cvt_pk_bf16_f32 v128, v17, v128
	v_cvt_pk_bf16_f32 v129, v19, v129
	v_cvt_pk_bf16_f32 v130, v21, v130
	v_cvt_pk_bf16_f32 v131, v23, v131
	global_store_dwordx4 v26, v[128:131], s[46:47]
	v_lshlrev_b32_e32 v16, 16, v140
	v_and_b32_e32 v140, s48, v140
	v_lshlrev_b32_e32 v17, 16, v136
	v_and_b32_e32 v136, s48, v136
	v_lshlrev_b32_e32 v18, 16, v141
	v_and_b32_e32 v141, s48, v141
	v_lshlrev_b32_e32 v19, 16, v137
	v_and_b32_e32 v137, s48, v137
	v_lshlrev_b32_e32 v20, 16, v142
	v_and_b32_e32 v142, s48, v142
	v_lshlrev_b32_e32 v21, 16, v138
	v_and_b32_e32 v138, s48, v138
	v_lshlrev_b32_e32 v22, 16, v143
	v_and_b32_e32 v143, s48, v143
	v_lshlrev_b32_e32 v23, 16, v139
	v_and_b32_e32 v139, s48, v139
	v_mul_f32_e32 v16, v24, v16
	v_mul_f32_e32 v140, v24, v140
	v_mul_f32_e32 v18, v24, v18
	v_mul_f32_e32 v141, v24, v141
	v_mul_f32_e32 v20, v24, v20
	v_mul_f32_e32 v142, v24, v142
	v_mul_f32_e32 v22, v24, v22
	v_mul_f32_e32 v143, v24, v143
	v_fmac_f32_e32 v17, v0, v16
	v_fmac_f32_e32 v136, v1, v140
	v_fmac_f32_e32 v19, v2, v18
	v_fmac_f32_e32 v137, v3, v141
	v_fmac_f32_e32 v21, v4, v20
	v_fmac_f32_e32 v138, v5, v142
	v_fmac_f32_e32 v23, v6, v22
	v_fmac_f32_e32 v139, v7, v143
	v_cvt_pk_bf16_f32 v136, v17, v136
	v_cvt_pk_bf16_f32 v137, v19, v137
	v_cvt_pk_bf16_f32 v138, v21, v138
	v_cvt_pk_bf16_f32 v139, v23, v139
	global_store_dwordx4 v26, v[136:139], s[46:47] offset:1024
	s_add_u32 s42, s12, 0x1c000
	s_addc_u32 s43, s13, 0
	global_load_dword v166, v27, s[42:43]
	s_add_u32 s14, s6, 0x3800000
	s_addc_u32 s15, s7, 0
	global_load_dwordx4 v[128:131], v26, s[14:15] nt
	global_load_dwordx4 v[136:139], v26, s[14:15] offset:1024 nt
	s_add_u32 s40, s8, 0x3800000
	s_addc_u32 s41, s9, 0
	global_load_dwordx4 v[132:135], v26, s[40:41] nt
	global_load_dwordx4 v[140:143], v26, s[40:41] offset:1024 nt
	s_waitcnt vmcnt(49)
	v_add_f32_dpp v167, v167, v167 row_ror:8 row_mask:0xf bank_mask:0xf
	s_nop 1
	v_add_f32_dpp v167, v167, v167 row_ror:4 row_mask:0xf bank_mask:0xf
	s_nop 1
	v_add_f32_dpp v167, v167, v167 row_ror:2 row_mask:0xf bank_mask:0xf
	s_nop 1
	v_add_f32_dpp v167, v167, v167 row_ror:1 row_mask:0xf bank_mask:0xf
	s_nop 1
	v_readfirstlane_b32 s44, v167
	s_add_u32 s46, s10, 0x1c00000
	s_addc_u32 s47, s11, 0
	v_mov_b32_e32 v25, s44
	v_fmamk_f32 v25, v25, 0x3a800000, v209
	v_rsq_f32_e32 v24, v25
	s_nop 0
	v_lshlrev_b32_e32 v16, 16, v148
	v_and_b32_e32 v148, s48, v148
	v_lshlrev_b32_e32 v17, 16, v144
	v_and_b32_e32 v144, s48, v144
	v_lshlrev_b32_e32 v18, 16, v149
	v_and_b32_e32 v149, s48, v149
	v_lshlrev_b32_e32 v19, 16, v145
	v_and_b32_e32 v145, s48, v145
	v_lshlrev_b32_e32 v20, 16, v150
	v_and_b32_e32 v150, s48, v150
	v_lshlrev_b32_e32 v21, 16, v146
	v_and_b32_e32 v146, s48, v146
	v_lshlrev_b32_e32 v22, 16, v151
	v_and_b32_e32 v151, s48, v151
	v_lshlrev_b32_e32 v23, 16, v147
	v_and_b32_e32 v147, s48, v147
	v_mul_f32_e32 v16, v24, v16
	v_mul_f32_e32 v148, v24, v148
	v_mul_f32_e32 v18, v24, v18
	v_mul_f32_e32 v149, v24, v149
	v_mul_f32_e32 v20, v24, v20
	v_mul_f32_e32 v150, v24, v150
	v_mul_f32_e32 v22, v24, v22
	v_mul_f32_e32 v151, v24, v151
	v_fmac_f32_e32 v17, v8, v16
	v_fmac_f32_e32 v144, v9, v148
	v_fmac_f32_e32 v19, v10, v18
	v_fmac_f32_e32 v145, v11, v149
	v_fmac_f32_e32 v21, v12, v20
	v_fmac_f32_e32 v146, v13, v150
	v_fmac_f32_e32 v23, v14, v22
	v_fmac_f32_e32 v147, v15, v151
	v_cvt_pk_bf16_f32 v144, v17, v144
	v_cvt_pk_bf16_f32 v145, v19, v145
	v_cvt_pk_bf16_f32 v146, v21, v146
	v_cvt_pk_bf16_f32 v147, v23, v147
	global_store_dwordx4 v26, v[144:147], s[46:47]
	v_lshlrev_b32_e32 v16, 16, v156
	v_and_b32_e32 v156, s48, v156
	v_lshlrev_b32_e32 v17, 16, v152
	v_and_b32_e32 v152, s48, v152
	v_lshlrev_b32_e32 v18, 16, v157
	v_and_b32_e32 v157, s48, v157
	v_lshlrev_b32_e32 v19, 16, v153
	v_and_b32_e32 v153, s48, v153
	v_lshlrev_b32_e32 v20, 16, v158
	v_and_b32_e32 v158, s48, v158
	v_lshlrev_b32_e32 v21, 16, v154
	v_and_b32_e32 v154, s48, v154
	v_lshlrev_b32_e32 v22, 16, v159
	v_and_b32_e32 v159, s48, v159
	v_lshlrev_b32_e32 v23, 16, v155
	v_and_b32_e32 v155, s48, v155
	v_mul_f32_e32 v16, v24, v16
	v_mul_f32_e32 v156, v24, v156
	v_mul_f32_e32 v18, v24, v18
	v_mul_f32_e32 v157, v24, v157
	v_mul_f32_e32 v20, v24, v20
	v_mul_f32_e32 v158, v24, v158
	v_mul_f32_e32 v22, v24, v22
	v_mul_f32_e32 v159, v24, v159
	v_fmac_f32_e32 v17, v0, v16
	v_fmac_f32_e32 v152, v1, v156
	v_fmac_f32_e32 v19, v2, v18
	v_fmac_f32_e32 v153, v3, v157
	v_fmac_f32_e32 v21, v4, v20
	v_fmac_f32_e32 v154, v5, v158
	v_fmac_f32_e32 v23, v6, v22
	v_fmac_f32_e32 v155, v7, v159
	v_cvt_pk_bf16_f32 v152, v17, v152
	v_cvt_pk_bf16_f32 v153, v19, v153
	v_cvt_pk_bf16_f32 v154, v21, v154
	v_cvt_pk_bf16_f32 v155, v23, v155
	global_store_dwordx4 v26, v[152:155], s[46:47] offset:1024
	s_add_u32 s42, s12, 0x1e000
	s_addc_u32 s43, s13, 0
	global_load_dword v167, v27, s[42:43]
	s_add_u32 s14, s6, 0x3c00000
	s_addc_u32 s15, s7, 0
	global_load_dwordx4 v[144:147], v26, s[14:15] nt
	global_load_dwordx4 v[152:155], v26, s[14:15] offset:1024 nt
	s_add_u32 s40, s8, 0x3c00000
	s_addc_u32 s41, s9, 0
	global_load_dwordx4 v[148:151], v26, s[40:41] nt
	global_load_dwordx4 v[156:159], v26, s[40:41] offset:1024 nt
	s_waitcnt vmcnt(49)
; __device__ void phase_x1(KP P, int layer) {
;     ...
;     for (int row = gw; row < MTOK; row += nw) {
;         const float rstd = rsqrtf(ssq2[row] * (1.f / 1024.f) + EPS);
;         if (lane == 0) ssq[row] = 0.f;
; #pragma unroll
;         for (int i = 0; i < 2; ++i) { const size_t off = (size_t)row * 1024 + lane * 8 + 512 * i;
;             float xv[8], mv[8]; unpack8(__builtin_nontemporal_load((const u32x4*)(xin + off)), xv); unpack8(__builtin_nontemporal_load((const u32x4*)(mix + off)), mv);
; #pragma unroll
;             for (int j = 0; j < 4; ++j) { xv[j] += mv[j] * rstd * wv[i][0][j]; xv[4 + j] += mv[4 + j] * rstd * wv[i][1][j]; }
;             *(u32x4*)(x1b + off) = __builtin_bit_cast(u32x4, pack8(xv)); }
	v_add_f32_dpp v160, v160, v160 row_ror:8 row_mask:0xf bank_mask:0xf
	s_nop 1
	v_add_f32_dpp v160, v160, v160 row_ror:4 row_mask:0xf bank_mask:0xf
	s_nop 1
	v_add_f32_dpp v160, v160, v160 row_ror:2 row_mask:0xf bank_mask:0xf
	s_nop 1
	v_add_f32_dpp v160, v160, v160 row_ror:1 row_mask:0xf bank_mask:0xf
	s_nop 1
	v_readfirstlane_b32 s44, v160
	s_add_u32 s46, s10, 0x2000000
	s_addc_u32 s47, s11, 0
	v_mov_b32_e32 v25, s44
	v_fmamk_f32 v25, v25, 0x3a800000, v209
	v_rsq_f32_e32 v24, v25
	s_nop 0
	v_lshlrev_b32_e32 v16, 16, v36
	v_and_b32_e32 v36, s48, v36
	v_lshlrev_b32_e32 v17, 16, v32
	v_and_b32_e32 v32, s48, v32
	v_lshlrev_b32_e32 v18, 16, v37
	v_and_b32_e32 v37, s48, v37
	v_lshlrev_b32_e32 v19, 16, v33
	v_and_b32_e32 v33, s48, v33
	v_lshlrev_b32_e32 v20, 16, v38
	v_and_b32_e32 v38, s48, v38
	v_lshlrev_b32_e32 v21, 16, v34
	v_and_b32_e32 v34, s48, v34
	v_lshlrev_b32_e32 v22, 16, v39
	v_and_b32_e32 v39, s48, v39
	v_lshlrev_b32_e32 v23, 16, v35
	v_and_b32_e32 v35, s48, v35
	v_mul_f32_e32 v16, v24, v16
	v_mul_f32_e32 v36, v24, v36
	v_mul_f32_e32 v18, v24, v18
	v_mul_f32_e32 v37, v24, v37
	v_mul_f32_e32 v20, v24, v20
	v_mul_f32_e32 v38, v24, v38
	v_mul_f32_e32 v22, v24, v22
	v_mul_f32_e32 v39, v24, v39
	v_fmac_f32_e32 v17, v8, v16
	v_fmac_f32_e32 v32, v9, v36
	v_fmac_f32_e32 v19, v10, v18
	v_fmac_f32_e32 v33, v11, v37
	v_fmac_f32_e32 v21, v12, v20
	v_fmac_f32_e32 v34, v13, v38
	v_fmac_f32_e32 v23, v14, v22
	v_fmac_f32_e32 v35, v15, v39
	v_cvt_pk_bf16_f32 v32, v17, v32
	v_cvt_pk_bf16_f32 v33, v19, v33
	v_cvt_pk_bf16_f32 v34, v21, v34
	v_cvt_pk_bf16_f32 v35, v23, v35
	global_store_dwordx4 v26, v[32:35], s[46:47]
	v_lshlrev_b32_e32 v16, 16, v44
	v_and_b32_e32 v44, s48, v44
	v_lshlrev_b32_e32 v17, 16, v40
	v_and_b32_e32 v40, s48, v40
	v_lshlrev_b32_e32 v18, 16, v45
	v_and_b32_e32 v45, s48, v45
	v_lshlrev_b32_e32 v19, 16, v41
	v_and_b32_e32 v41, s48, v41
	v_lshlrev_b32_e32 v20, 16, v46
	v_and_b32_e32 v46, s48, v46
	v_lshlrev_b32_e32 v21, 16, v42
	v_and_b32_e32 v42, s48, v42
	v_lshlrev_b32_e32 v22, 16, v47
	v_and_b32_e32 v47, s48, v47
	v_lshlrev_b32_e32 v23, 16, v43
	v_and_b32_e32 v43, s48, v43
	v_mul_f32_e32 v16, v24, v16
	v_mul_f32_e32 v44, v24, v44
	v_mul_f32_e32 v18, v24, v18
	v_mul_f32_e32 v45, v24, v45
	v_mul_f32_e32 v20, v24, v20
	v_mul_f32_e32 v46, v24, v46
	v_mul_f32_e32 v22, v24, v22
	v_mul_f32_e32 v47, v24, v47
	v_fmac_f32_e32 v17, v0, v16
	v_fmac_f32_e32 v40, v1, v44
	v_fmac_f32_e32 v19, v2, v18
	v_fmac_f32_e32 v41, v3, v45
	v_fmac_f32_e32 v21, v4, v20
	v_fmac_f32_e32 v42, v5, v46
	v_fmac_f32_e32 v23, v6, v22
	v_fmac_f32_e32 v43, v7, v47
	v_cvt_pk_bf16_f32 v40, v17, v40
	v_cvt_pk_bf16_f32 v41, v19, v41
	v_cvt_pk_bf16_f32 v42, v21, v42
	v_cvt_pk_bf16_f32 v43, v23, v43
	global_store_dwordx4 v26, v[40:43], s[46:47] offset:1024
	s_waitcnt vmcnt(44)
	v_add_f32_dpp v161, v161, v161 row_ror:8 row_mask:0xf bank_mask:0xf
	s_nop 1
	v_add_f32_dpp v161, v161, v161 row_ror:4 row_mask:0xf bank_mask:0xf
	s_nop 1
	v_add_f32_dpp v161, v161, v161 row_ror:2 row_mask:0xf bank_mask:0xf
	s_nop 1
	v_add_f32_dpp v161, v161, v161 row_ror:1 row_mask:0xf bank_mask:0xf
	s_nop 1
	v_readfirstlane_b32 s44, v161
	s_add_u32 s46, s10, 0x2400000
	s_addc_u32 s47, s11, 0
	v_mov_b32_e32 v25, s44
	v_fmamk_f32 v25, v25, 0x3a800000, v209
	v_rsq_f32_e32 v24, v25
	s_nop 0
	v_lshlrev_b32_e32 v16, 16, v52
	v_and_b32_e32 v52, s48, v52
	v_lshlrev_b32_e32 v17, 16, v48
	v_and_b32_e32 v48, s48, v48
	v_lshlrev_b32_e32 v18, 16, v53
	v_and_b32_e32 v53, s48, v53
	v_lshlrev_b32_e32 v19, 16, v49
	v_and_b32_e32 v49, s48, v49
	v_lshlrev_b32_e32 v20, 16, v54
	v_and_b32_e32 v54, s48, v54
	v_lshlrev_b32_e32 v21, 16, v50
	v_and_b32_e32 v50, s48, v50
	v_lshlrev_b32_e32 v22, 16, v55
	v_and_b32_e32 v55, s48, v55
	v_lshlrev_b32_e32 v23, 16, v51
	v_and_b32_e32 v51, s48, v51
	v_mul_f32_e32 v16, v24, v16
	v_mul_f32_e32 v52, v24, v52
	v_mul_f32_e32 v18, v24, v18
	v_mul_f32_e32 v53, v24, v53
	v_mul_f32_e32 v20, v24, v20
	v_mul_f32_e32 v54, v24, v54
	v_mul_f32_e32 v22, v24, v22
	v_mul_f32_e32 v55, v24, v55
	v_fmac_f32_e32 v17, v8, v16
	v_fmac_f32_e32 v48, v9, v52
	v_fmac_f32_e32 v19, v10, v18
	v_fmac_f32_e32 v49, v11, v53
	v_fmac_f32_e32 v21, v12, v20
	v_fmac_f32_e32 v50, v13, v54
	v_fmac_f32_e32 v23, v14, v22
	v_fmac_f32_e32 v51, v15, v55
	v_cvt_pk_bf16_f32 v48, v17, v48
	v_cvt_pk_bf16_f32 v49, v19, v49
	v_cvt_pk_bf16_f32 v50, v21, v50
	v_cvt_pk_bf16_f32 v51, v23, v51
	global_store_dwordx4 v26, v[48:51], s[46:47]
	v_lshlrev_b32_e32 v16, 16, v60
	v_and_b32_e32 v60, s48, v60
	v_lshlrev_b32_e32 v17, 16, v56
	v_and_b32_e32 v56, s48, v56
	v_lshlrev_b32_e32 v18, 16, v61
	v_and_b32_e32 v61, s48, v61
	v_lshlrev_b32_e32 v19, 16, v57
	v_and_b32_e32 v57, s48, v57
	v_lshlrev_b32_e32 v20, 16, v62
	v_and_b32_e32 v62, s48, v62
	v_lshlrev_b32_e32 v21, 16, v58
	v_and_b32_e32 v58, s48, v58
	v_lshlrev_b32_e32 v22, 16, v63
	v_and_b32_e32 v63, s48, v63
	v_lshlrev_b32_e32 v23, 16, v59
	v_and_b32_e32 v59, s48, v59
	v_mul_f32_e32 v16, v24, v16
	v_mul_f32_e32 v60, v24, v60
	v_mul_f32_e32 v18, v24, v18
	v_mul_f32_e32 v61, v24, v61
	v_mul_f32_e32 v20, v24, v20
	v_mul_f32_e32 v62, v24, v62
	v_mul_f32_e32 v22, v24, v22
	v_mul_f32_e32 v63, v24, v63
	v_fmac_f32_e32 v17, v0, v16
	v_fmac_f32_e32 v56, v1, v60
	v_fmac_f32_e32 v19, v2, v18
	v_fmac_f32_e32 v57, v3, v61
	v_fmac_f32_e32 v21, v4, v20
	v_fmac_f32_e32 v58, v5, v62
	v_fmac_f32_e32 v23, v6, v22
	v_fmac_f32_e32 v59, v7, v63
	v_cvt_pk_bf16_f32 v56, v17, v56
	v_cvt_pk_bf16_f32 v57, v19, v57
	v_cvt_pk_bf16_f32 v58, v21, v58
	v_cvt_pk_bf16_f32 v59, v23, v59
	global_store_dwordx4 v26, v[56:59], s[46:47] offset:1024
	s_waitcnt vmcnt(39)
; __device__ void phase_x1(KP P, int layer) {
;     ...
;     for (int row = gw; row < MTOK; row += nw) {
;         const float rstd = rsqrtf(ssq2[row] * (1.f / 1024.f) + EPS);
;         if (lane == 0) ssq[row] = 0.f;
; #pragma unroll
;         for (int i = 0; i < 2; ++i) { const size_t off = (size_t)row * 1024 + lane * 8 + 512 * i;
;             float xv[8], mv[8]; unpack8(__builtin_nontemporal_load((const u32x4*)(xin + off)), xv); unpack8(__builtin_nontemporal_load((const u32x4*)(mix + off)), mv);
; #pragma unroll
;             for (int j = 0; j < 4; ++j) { xv[j] += mv[j] * rstd * wv[i][0][j]; xv[4 + j] += mv[4 + j] * rstd * wv[i][1][j]; }
;             *(u32x4*)(x1b + off) = __builtin_bit_cast(u32x4, pack8(xv)); }
	v_add_f32_dpp v162, v162, v162 row_ror:8 row_mask:0xf bank_mask:0xf
	s_nop 1
	v_add_f32_dpp v162, v162, v162 row_ror:4 row_mask:0xf bank_mask:0xf
	s_nop 1
	v_add_f32_dpp v162, v162, v162 row_ror:2 row_mask:0xf bank_mask:0xf
	s_nop 1
	v_add_f32_dpp v162, v162, v162 row_ror:1 row_mask:0xf bank_mask:0xf
	s_nop 1
	v_readfirstlane_b32 s44, v162
	s_add_u32 s46, s10, 0x2800000
	s_addc_u32 s47, s11, 0
	v_mov_b32_e32 v25, s44
	v_fmamk_f32 v25, v25, 0x3a800000, v209
	v_rsq_f32_e32 v24, v25
	s_nop 0
	v_lshlrev_b32_e32 v16, 16, v68
	v_and_b32_e32 v68, s48, v68
	v_lshlrev_b32_e32 v17, 16, v64
	v_and_b32_e32 v64, s48, v64
	v_lshlrev_b32_e32 v18, 16, v69
	v_and_b32_e32 v69, s48, v69
	v_lshlrev_b32_e32 v19, 16, v65
	v_and_b32_e32 v65, s48, v65
	v_lshlrev_b32_e32 v20, 16, v70
	v_and_b32_e32 v70, s48, v70
	v_lshlrev_b32_e32 v21, 16, v66
	v_and_b32_e32 v66, s48, v66
	v_lshlrev_b32_e32 v22, 16, v71
	v_and_b32_e32 v71, s48, v71
	v_lshlrev_b32_e32 v23, 16, v67
	v_and_b32_e32 v67, s48, v67
	v_mul_f32_e32 v16, v24, v16
	v_mul_f32_e32 v68, v24, v68
	v_mul_f32_e32 v18, v24, v18
	v_mul_f32_e32 v69, v24, v69
	v_mul_f32_e32 v20, v24, v20
	v_mul_f32_e32 v70, v24, v70
	v_mul_f32_e32 v22, v24, v22
	v_mul_f32_e32 v71, v24, v71
	v_fmac_f32_e32 v17, v8, v16
	v_fmac_f32_e32 v64, v9, v68
	v_fmac_f32_e32 v19, v10, v18
	v_fmac_f32_e32 v65, v11, v69
	v_fmac_f32_e32 v21, v12, v20
	v_fmac_f32_e32 v66, v13, v70
	v_fmac_f32_e32 v23, v14, v22
	v_fmac_f32_e32 v67, v15, v71
	v_cvt_pk_bf16_f32 v64, v17, v64
	v_cvt_pk_bf16_f32 v65, v19, v65
	v_cvt_pk_bf16_f32 v66, v21, v66
	v_cvt_pk_bf16_f32 v67, v23, v67
	global_store_dwordx4 v26, v[64:67], s[46:47]
	v_lshlrev_b32_e32 v16, 16, v76
	v_and_b32_e32 v76, s48, v76
	v_lshlrev_b32_e32 v17, 16, v72
	v_and_b32_e32 v72, s48, v72
	v_lshlrev_b32_e32 v18, 16, v77
	v_and_b32_e32 v77, s48, v77
	v_lshlrev_b32_e32 v19, 16, v73
	v_and_b32_e32 v73, s48, v73
	v_lshlrev_b32_e32 v20, 16, v78
	v_and_b32_e32 v78, s48, v78
	v_lshlrev_b32_e32 v21, 16, v74
	v_and_b32_e32 v74, s48, v74
	v_lshlrev_b32_e32 v22, 16, v79
	v_and_b32_e32 v79, s48, v79
	v_lshlrev_b32_e32 v23, 16, v75
	v_and_b32_e32 v75, s48, v75
	v_mul_f32_e32 v16, v24, v16
	v_mul_f32_e32 v76, v24, v76
	v_mul_f32_e32 v18, v24, v18
	v_mul_f32_e32 v77, v24, v77
	v_mul_f32_e32 v20, v24, v20
	v_mul_f32_e32 v78, v24, v78
	v_mul_f32_e32 v22, v24, v22
	v_mul_f32_e32 v79, v24, v79
	v_fmac_f32_e32 v17, v0, v16
	v_fmac_f32_e32 v72, v1, v76
	v_fmac_f32_e32 v19, v2, v18
	v_fmac_f32_e32 v73, v3, v77
	v_fmac_f32_e32 v21, v4, v20
	v_fmac_f32_e32 v74, v5, v78
	v_fmac_f32_e32 v23, v6, v22
	v_fmac_f32_e32 v75, v7, v79
	v_cvt_pk_bf16_f32 v72, v17, v72
	v_cvt_pk_bf16_f32 v73, v19, v73
	v_cvt_pk_bf16_f32 v74, v21, v74
	v_cvt_pk_bf16_f32 v75, v23, v75
	global_store_dwordx4 v26, v[72:75], s[46:47] offset:1024
	s_waitcnt vmcnt(34)
	v_add_f32_dpp v163, v163, v163 row_ror:8 row_mask:0xf bank_mask:0xf
	s_nop 1
	v_add_f32_dpp v163, v163, v163 row_ror:4 row_mask:0xf bank_mask:0xf
	s_nop 1
	v_add_f32_dpp v163, v163, v163 row_ror:2 row_mask:0xf bank_mask:0xf
	s_nop 1
	v_add_f32_dpp v163, v163, v163 row_ror:1 row_mask:0xf bank_mask:0xf
	s_nop 1
	v_readfirstlane_b32 s44, v163
	s_add_u32 s46, s10, 0x2c00000
	s_addc_u32 s47, s11, 0
	v_mov_b32_e32 v25, s44
	v_fmamk_f32 v25, v25, 0x3a800000, v209
	v_rsq_f32_e32 v24, v25
	s_nop 0
	v_lshlrev_b32_e32 v16, 16, v84
	v_and_b32_e32 v84, s48, v84
	v_lshlrev_b32_e32 v17, 16, v80
	v_and_b32_e32 v80, s48, v80
	v_lshlrev_b32_e32 v18, 16, v85
	v_and_b32_e32 v85, s48, v85
	v_lshlrev_b32_e32 v19, 16, v81
	v_and_b32_e32 v81, s48, v81
	v_lshlrev_b32_e32 v20, 16, v86
	v_and_b32_e32 v86, s48, v86
	v_lshlrev_b32_e32 v21, 16, v82
	v_and_b32_e32 v82, s48, v82
	v_lshlrev_b32_e32 v22, 16, v87
	v_and_b32_e32 v87, s48, v87
	v_lshlrev_b32_e32 v23, 16, v83
	v_and_b32_e32 v83, s48, v83
	v_mul_f32_e32 v16, v24, v16
	v_mul_f32_e32 v84, v24, v84
	v_mul_f32_e32 v18, v24, v18
	v_mul_f32_e32 v85, v24, v85
	v_mul_f32_e32 v20, v24, v20
	v_mul_f32_e32 v86, v24, v86
	v_mul_f32_e32 v22, v24, v22
	v_mul_f32_e32 v87, v24, v87
	v_fmac_f32_e32 v17, v8, v16
	v_fmac_f32_e32 v80, v9, v84
	v_fmac_f32_e32 v19, v10, v18
	v_fmac_f32_e32 v81, v11, v85
	v_fmac_f32_e32 v21, v12, v20
	v_fmac_f32_e32 v82, v13, v86
	v_fmac_f32_e32 v23, v14, v22
	v_fmac_f32_e32 v83, v15, v87
	v_cvt_pk_bf16_f32 v80, v17, v80
	v_cvt_pk_bf16_f32 v81, v19, v81
	v_cvt_pk_bf16_f32 v82, v21, v82
	v_cvt_pk_bf16_f32 v83, v23, v83
	global_store_dwordx4 v26, v[80:83], s[46:47]
	v_lshlrev_b32_e32 v16, 16, v92
	v_and_b32_e32 v92, s48, v92
	v_lshlrev_b32_e32 v17, 16, v88
	v_and_b32_e32 v88, s48, v88
	v_lshlrev_b32_e32 v18, 16, v93
	v_and_b32_e32 v93, s48, v93
	v_lshlrev_b32_e32 v19, 16, v89
	v_and_b32_e32 v89, s48, v89
	v_lshlrev_b32_e32 v20, 16, v94
	v_and_b32_e32 v94, s48, v94
	v_lshlrev_b32_e32 v21, 16, v90
	v_and_b32_e32 v90, s48, v90
	v_lshlrev_b32_e32 v22, 16, v95
	v_and_b32_e32 v95, s48, v95
	v_lshlrev_b32_e32 v23, 16, v91
	v_and_b32_e32 v91, s48, v91
	v_mul_f32_e32 v16, v24, v16
	v_mul_f32_e32 v92, v24, v92
	v_mul_f32_e32 v18, v24, v18
	v_mul_f32_e32 v93, v24, v93
	v_mul_f32_e32 v20, v24, v20
	v_mul_f32_e32 v94, v24, v94
	v_mul_f32_e32 v22, v24, v22
	v_mul_f32_e32 v95, v24, v95
	v_fmac_f32_e32 v17, v0, v16
	v_fmac_f32_e32 v88, v1, v92
	v_fmac_f32_e32 v19, v2, v18
	v_fmac_f32_e32 v89, v3, v93
	v_fmac_f32_e32 v21, v4, v20
	v_fmac_f32_e32 v90, v5, v94
	v_fmac_f32_e32 v23, v6, v22
	v_fmac_f32_e32 v91, v7, v95
	v_cvt_pk_bf16_f32 v88, v17, v88
	v_cvt_pk_bf16_f32 v89, v19, v89
	v_cvt_pk_bf16_f32 v90, v21, v90
	v_cvt_pk_bf16_f32 v91, v23, v91
	global_store_dwordx4 v26, v[88:91], s[46:47] offset:1024
	s_waitcnt vmcnt(29)
; __device__ void phase_x1(KP P, int layer) {
;     ...
;     for (int row = gw; row < MTOK; row += nw) {
;         const float rstd = rsqrtf(ssq2[row] * (1.f / 1024.f) + EPS);
;         if (lane == 0) ssq[row] = 0.f;
; #pragma unroll
;         for (int i = 0; i < 2; ++i) { const size_t off = (size_t)row * 1024 + lane * 8 + 512 * i;
;             float xv[8], mv[8]; unpack8(__builtin_nontemporal_load((const u32x4*)(xin + off)), xv); unpack8(__builtin_nontemporal_load((const u32x4*)(mix + off)), mv);
; #pragma unroll
;             for (int j = 0; j < 4; ++j) { xv[j] += mv[j] * rstd * wv[i][0][j]; xv[4 + j] += mv[4 + j] * rstd * wv[i][1][j]; }
;             *(u32x4*)(x1b + off) = __builtin_bit_cast(u32x4, pack8(xv)); }
	v_add_f32_dpp v164, v164, v164 row_ror:8 row_mask:0xf bank_mask:0xf
	s_nop 1
	v_add_f32_dpp v164, v164, v164 row_ror:4 row_mask:0xf bank_mask:0xf
	s_nop 1
	v_add_f32_dpp v164, v164, v164 row_ror:2 row_mask:0xf bank_mask:0xf
	s_nop 1
	v_add_f32_dpp v164, v164, v164 row_ror:1 row_mask:0xf bank_mask:0xf
	s_nop 1
	v_readfirstlane_b32 s44, v164
	s_add_u32 s46, s10, 0x3000000
	s_addc_u32 s47, s11, 0
	v_mov_b32_e32 v25, s44
	v_fmamk_f32 v25, v25, 0x3a800000, v209
	v_rsq_f32_e32 v24, v25
	s_nop 0
	v_lshlrev_b32_e32 v16, 16, v100
	v_and_b32_e32 v100, s48, v100
	v_lshlrev_b32_e32 v17, 16, v96
	v_and_b32_e32 v96, s48, v96
	v_lshlrev_b32_e32 v18, 16, v101
	v_and_b32_e32 v101, s48, v101
	v_lshlrev_b32_e32 v19, 16, v97
	v_and_b32_e32 v97, s48, v97
	v_lshlrev_b32_e32 v20, 16, v102
	v_and_b32_e32 v102, s48, v102
	v_lshlrev_b32_e32 v21, 16, v98
	v_and_b32_e32 v98, s48, v98
	v_lshlrev_b32_e32 v22, 16, v103
	v_and_b32_e32 v103, s48, v103
	v_lshlrev_b32_e32 v23, 16, v99
	v_and_b32_e32 v99, s48, v99
	v_mul_f32_e32 v16, v24, v16
	v_mul_f32_e32 v100, v24, v100
	v_mul_f32_e32 v18, v24, v18
	v_mul_f32_e32 v101, v24, v101
	v_mul_f32_e32 v20, v24, v20
	v_mul_f32_e32 v102, v24, v102
	v_mul_f32_e32 v22, v24, v22
	v_mul_f32_e32 v103, v24, v103
	v_fmac_f32_e32 v17, v8, v16
	v_fmac_f32_e32 v96, v9, v100
	v_fmac_f32_e32 v19, v10, v18
	v_fmac_f32_e32 v97, v11, v101
	v_fmac_f32_e32 v21, v12, v20
	v_fmac_f32_e32 v98, v13, v102
	v_fmac_f32_e32 v23, v14, v22
	v_fmac_f32_e32 v99, v15, v103
	v_cvt_pk_bf16_f32 v96, v17, v96
	v_cvt_pk_bf16_f32 v97, v19, v97
	v_cvt_pk_bf16_f32 v98, v21, v98
	v_cvt_pk_bf16_f32 v99, v23, v99
	global_store_dwordx4 v26, v[96:99], s[46:47]
	v_lshlrev_b32_e32 v16, 16, v108
	v_and_b32_e32 v108, s48, v108
	v_lshlrev_b32_e32 v17, 16, v104
	v_and_b32_e32 v104, s48, v104
	v_lshlrev_b32_e32 v18, 16, v109
	v_and_b32_e32 v109, s48, v109
	v_lshlrev_b32_e32 v19, 16, v105
	v_and_b32_e32 v105, s48, v105
	v_lshlrev_b32_e32 v20, 16, v110
	v_and_b32_e32 v110, s48, v110
	v_lshlrev_b32_e32 v21, 16, v106
	v_and_b32_e32 v106, s48, v106
	v_lshlrev_b32_e32 v22, 16, v111
	v_and_b32_e32 v111, s48, v111
	v_lshlrev_b32_e32 v23, 16, v107
	v_and_b32_e32 v107, s48, v107
	v_mul_f32_e32 v16, v24, v16
	v_mul_f32_e32 v108, v24, v108
	v_mul_f32_e32 v18, v24, v18
	v_mul_f32_e32 v109, v24, v109
	v_mul_f32_e32 v20, v24, v20
	v_mul_f32_e32 v110, v24, v110
	v_mul_f32_e32 v22, v24, v22
	v_mul_f32_e32 v111, v24, v111
	v_fmac_f32_e32 v17, v0, v16
	v_fmac_f32_e32 v104, v1, v108
	v_fmac_f32_e32 v19, v2, v18
	v_fmac_f32_e32 v105, v3, v109
	v_fmac_f32_e32 v21, v4, v20
	v_fmac_f32_e32 v106, v5, v110
	v_fmac_f32_e32 v23, v6, v22
	v_fmac_f32_e32 v107, v7, v111
	v_cvt_pk_bf16_f32 v104, v17, v104
	v_cvt_pk_bf16_f32 v105, v19, v105
	v_cvt_pk_bf16_f32 v106, v21, v106
	v_cvt_pk_bf16_f32 v107, v23, v107
	global_store_dwordx4 v26, v[104:107], s[46:47] offset:1024
	s_waitcnt vmcnt(24)
	v_add_f32_dpp v165, v165, v165 row_ror:8 row_mask:0xf bank_mask:0xf
	s_nop 1
	v_add_f32_dpp v165, v165, v165 row_ror:4 row_mask:0xf bank_mask:0xf
	s_nop 1
	v_add_f32_dpp v165, v165, v165 row_ror:2 row_mask:0xf bank_mask:0xf
	s_nop 1
	v_add_f32_dpp v165, v165, v165 row_ror:1 row_mask:0xf bank_mask:0xf
	s_nop 1
	v_readfirstlane_b32 s44, v165
	s_add_u32 s46, s10, 0x3400000
	s_addc_u32 s47, s11, 0
	v_mov_b32_e32 v25, s44
	v_fmamk_f32 v25, v25, 0x3a800000, v209
	v_rsq_f32_e32 v24, v25
	s_nop 0
	v_lshlrev_b32_e32 v16, 16, v116
	v_and_b32_e32 v116, s48, v116
	v_lshlrev_b32_e32 v17, 16, v112
	v_and_b32_e32 v112, s48, v112
	v_lshlrev_b32_e32 v18, 16, v117
	v_and_b32_e32 v117, s48, v117
	v_lshlrev_b32_e32 v19, 16, v113
	v_and_b32_e32 v113, s48, v113
	v_lshlrev_b32_e32 v20, 16, v118
	v_and_b32_e32 v118, s48, v118
	v_lshlrev_b32_e32 v21, 16, v114
	v_and_b32_e32 v114, s48, v114
	v_lshlrev_b32_e32 v22, 16, v119
	v_and_b32_e32 v119, s48, v119
	v_lshlrev_b32_e32 v23, 16, v115
	v_and_b32_e32 v115, s48, v115
	v_mul_f32_e32 v16, v24, v16
	v_mul_f32_e32 v116, v24, v116
	v_mul_f32_e32 v18, v24, v18
	v_mul_f32_e32 v117, v24, v117
	v_mul_f32_e32 v20, v24, v20
	v_mul_f32_e32 v118, v24, v118
	v_mul_f32_e32 v22, v24, v22
	v_mul_f32_e32 v119, v24, v119
	v_fmac_f32_e32 v17, v8, v16
	v_fmac_f32_e32 v112, v9, v116
	v_fmac_f32_e32 v19, v10, v18
	v_fmac_f32_e32 v113, v11, v117
	v_fmac_f32_e32 v21, v12, v20
	v_fmac_f32_e32 v114, v13, v118
	v_fmac_f32_e32 v23, v14, v22
	v_fmac_f32_e32 v115, v15, v119
	v_cvt_pk_bf16_f32 v112, v17, v112
	v_cvt_pk_bf16_f32 v113, v19, v113
	v_cvt_pk_bf16_f32 v114, v21, v114
	v_cvt_pk_bf16_f32 v115, v23, v115
	global_store_dwordx4 v26, v[112:115], s[46:47]
	v_lshlrev_b32_e32 v16, 16, v124
	v_and_b32_e32 v124, s48, v124
	v_lshlrev_b32_e32 v17, 16, v120
	v_and_b32_e32 v120, s48, v120
	v_lshlrev_b32_e32 v18, 16, v125
	v_and_b32_e32 v125, s48, v125
	v_lshlrev_b32_e32 v19, 16, v121
	v_and_b32_e32 v121, s48, v121
	v_lshlrev_b32_e32 v20, 16, v126
	v_and_b32_e32 v126, s48, v126
	v_lshlrev_b32_e32 v21, 16, v122
	v_and_b32_e32 v122, s48, v122
	v_lshlrev_b32_e32 v22, 16, v127
	v_and_b32_e32 v127, s48, v127
	v_lshlrev_b32_e32 v23, 16, v123
	v_and_b32_e32 v123, s48, v123
	v_mul_f32_e32 v16, v24, v16
	v_mul_f32_e32 v124, v24, v124
	v_mul_f32_e32 v18, v24, v18
	v_mul_f32_e32 v125, v24, v125
	v_mul_f32_e32 v20, v24, v20
	v_mul_f32_e32 v126, v24, v126
	v_mul_f32_e32 v22, v24, v22
	v_mul_f32_e32 v127, v24, v127
	v_fmac_f32_e32 v17, v0, v16
	v_fmac_f32_e32 v120, v1, v124
	v_fmac_f32_e32 v19, v2, v18
	v_fmac_f32_e32 v121, v3, v125
	v_fmac_f32_e32 v21, v4, v20
	v_fmac_f32_e32 v122, v5, v126
	v_fmac_f32_e32 v23, v6, v22
	v_fmac_f32_e32 v123, v7, v127
	v_cvt_pk_bf16_f32 v120, v17, v120
	v_cvt_pk_bf16_f32 v121, v19, v121
	v_cvt_pk_bf16_f32 v122, v21, v122
	v_cvt_pk_bf16_f32 v123, v23, v123
	global_store_dwordx4 v26, v[120:123], s[46:47] offset:1024
	s_waitcnt vmcnt(19)
; __device__ void phase_x1(KP P, int layer) {
;     ...
;     for (int row = gw; row < MTOK; row += nw) {
;         const float rstd = rsqrtf(ssq2[row] * (1.f / 1024.f) + EPS);
;         if (lane == 0) ssq[row] = 0.f;
; #pragma unroll
;         for (int i = 0; i < 2; ++i) { const size_t off = (size_t)row * 1024 + lane * 8 + 512 * i;
;             float xv[8], mv[8]; unpack8(__builtin_nontemporal_load((const u32x4*)(xin + off)), xv); unpack8(__builtin_nontemporal_load((const u32x4*)(mix + off)), mv);
; #pragma unroll
;             for (int j = 0; j < 4; ++j) { xv[j] += mv[j] * rstd * wv[i][0][j]; xv[4 + j] += mv[4 + j] * rstd * wv[i][1][j]; }
;             *(u32x4*)(x1b + off) = __builtin_bit_cast(u32x4, pack8(xv)); }
	v_add_f32_dpp v166, v166, v166 row_ror:8 row_mask:0xf bank_mask:0xf
	s_nop 1
	v_add_f32_dpp v166, v166, v166 row_ror:4 row_mask:0xf bank_mask:0xf
	s_nop 1
	v_add_f32_dpp v166, v166, v166 row_ror:2 row_mask:0xf bank_mask:0xf
	s_nop 1
	v_add_f32_dpp v166, v166, v166 row_ror:1 row_mask:0xf bank_mask:0xf
	s_nop 1
	v_readfirstlane_b32 s44, v166
	s_add_u32 s46, s10, 0x3800000
	s_addc_u32 s47, s11, 0
	v_mov_b32_e32 v25, s44
	v_fmamk_f32 v25, v25, 0x3a800000, v209
	v_rsq_f32_e32 v24, v25
	s_nop 0
	v_lshlrev_b32_e32 v16, 16, v132
	v_and_b32_e32 v132, s48, v132
	v_lshlrev_b32_e32 v17, 16, v128
	v_and_b32_e32 v128, s48, v128
	v_lshlrev_b32_e32 v18, 16, v133
	v_and_b32_e32 v133, s48, v133
	v_lshlrev_b32_e32 v19, 16, v129
	v_and_b32_e32 v129, s48, v129
	v_lshlrev_b32_e32 v20, 16, v134
	v_and_b32_e32 v134, s48, v134
	v_lshlrev_b32_e32 v21, 16, v130
	v_and_b32_e32 v130, s48, v130
	v_lshlrev_b32_e32 v22, 16, v135
	v_and_b32_e32 v135, s48, v135
	v_lshlrev_b32_e32 v23, 16, v131
	v_and_b32_e32 v131, s48, v131
	v_mul_f32_e32 v16, v24, v16
	v_mul_f32_e32 v132, v24, v132
	v_mul_f32_e32 v18, v24, v18
	v_mul_f32_e32 v133, v24, v133
	v_mul_f32_e32 v20, v24, v20
	v_mul_f32_e32 v134, v24, v134
	v_mul_f32_e32 v22, v24, v22
	v_mul_f32_e32 v135, v24, v135
	v_fmac_f32_e32 v17, v8, v16
	v_fmac_f32_e32 v128, v9, v132
	v_fmac_f32_e32 v19, v10, v18
	v_fmac_f32_e32 v129, v11, v133
	v_fmac_f32_e32 v21, v12, v20
	v_fmac_f32_e32 v130, v13, v134
	v_fmac_f32_e32 v23, v14, v22
	v_fmac_f32_e32 v131, v15, v135
	v_cvt_pk_bf16_f32 v128, v17, v128
	v_cvt_pk_bf16_f32 v129, v19, v129
	v_cvt_pk_bf16_f32 v130, v21, v130
	v_cvt_pk_bf16_f32 v131, v23, v131
	global_store_dwordx4 v26, v[128:131], s[46:47]
	v_lshlrev_b32_e32 v16, 16, v140
	v_and_b32_e32 v140, s48, v140
	v_lshlrev_b32_e32 v17, 16, v136
	v_and_b32_e32 v136, s48, v136
	v_lshlrev_b32_e32 v18, 16, v141
	v_and_b32_e32 v141, s48, v141
	v_lshlrev_b32_e32 v19, 16, v137
	v_and_b32_e32 v137, s48, v137
	v_lshlrev_b32_e32 v20, 16, v142
	v_and_b32_e32 v142, s48, v142
	v_lshlrev_b32_e32 v21, 16, v138
	v_and_b32_e32 v138, s48, v138
	v_lshlrev_b32_e32 v22, 16, v143
	v_and_b32_e32 v143, s48, v143
	v_lshlrev_b32_e32 v23, 16, v139
	v_and_b32_e32 v139, s48, v139
	v_mul_f32_e32 v16, v24, v16
	v_mul_f32_e32 v140, v24, v140
	v_mul_f32_e32 v18, v24, v18
	v_mul_f32_e32 v141, v24, v141
	v_mul_f32_e32 v20, v24, v20
	v_mul_f32_e32 v142, v24, v142
	v_mul_f32_e32 v22, v24, v22
	v_mul_f32_e32 v143, v24, v143
	v_fmac_f32_e32 v17, v0, v16
	v_fmac_f32_e32 v136, v1, v140
	v_fmac_f32_e32 v19, v2, v18
	v_fmac_f32_e32 v137, v3, v141
	v_fmac_f32_e32 v21, v4, v20
	v_fmac_f32_e32 v138, v5, v142
	v_fmac_f32_e32 v23, v6, v22
	v_fmac_f32_e32 v139, v7, v143
	v_cvt_pk_bf16_f32 v136, v17, v136
	v_cvt_pk_bf16_f32 v137, v19, v137
	v_cvt_pk_bf16_f32 v138, v21, v138
	v_cvt_pk_bf16_f32 v139, v23, v139
	global_store_dwordx4 v26, v[136:139], s[46:47] offset:1024
	s_waitcnt vmcnt(14)
	v_add_f32_dpp v167, v167, v167 row_ror:8 row_mask:0xf bank_mask:0xf
	s_nop 1
	v_add_f32_dpp v167, v167, v167 row_ror:4 row_mask:0xf bank_mask:0xf
	s_nop 1
	v_add_f32_dpp v167, v167, v167 row_ror:2 row_mask:0xf bank_mask:0xf
	s_nop 1
	v_add_f32_dpp v167, v167, v167 row_ror:1 row_mask:0xf bank_mask:0xf
	s_nop 1
	v_readfirstlane_b32 s44, v167
	s_add_u32 s46, s10, 0x3c00000
	s_addc_u32 s47, s11, 0
	v_mov_b32_e32 v25, s44
	v_fmamk_f32 v25, v25, 0x3a800000, v209
	v_rsq_f32_e32 v24, v25
	s_nop 0
	v_lshlrev_b32_e32 v16, 16, v148
	v_and_b32_e32 v148, s48, v148
	v_lshlrev_b32_e32 v17, 16, v144
	v_and_b32_e32 v144, s48, v144
	v_lshlrev_b32_e32 v18, 16, v149
	v_and_b32_e32 v149, s48, v149
	v_lshlrev_b32_e32 v19, 16, v145
	v_and_b32_e32 v145, s48, v145
	v_lshlrev_b32_e32 v20, 16, v150
	v_and_b32_e32 v150, s48, v150
	v_lshlrev_b32_e32 v21, 16, v146
	v_and_b32_e32 v146, s48, v146
	v_lshlrev_b32_e32 v22, 16, v151
	v_and_b32_e32 v151, s48, v151
	v_lshlrev_b32_e32 v23, 16, v147
	v_and_b32_e32 v147, s48, v147
	v_mul_f32_e32 v16, v24, v16
	v_mul_f32_e32 v148, v24, v148
	v_mul_f32_e32 v18, v24, v18
	v_mul_f32_e32 v149, v24, v149
	v_mul_f32_e32 v20, v24, v20
	v_mul_f32_e32 v150, v24, v150
	v_mul_f32_e32 v22, v24, v22
	v_mul_f32_e32 v151, v24, v151
	v_fmac_f32_e32 v17, v8, v16
	v_fmac_f32_e32 v144, v9, v148
	v_fmac_f32_e32 v19, v10, v18
	v_fmac_f32_e32 v145, v11, v149
	v_fmac_f32_e32 v21, v12, v20
	v_fmac_f32_e32 v146, v13, v150
	v_fmac_f32_e32 v23, v14, v22
	v_fmac_f32_e32 v147, v15, v151
	v_cvt_pk_bf16_f32 v144, v17, v144
	v_cvt_pk_bf16_f32 v145, v19, v145
	v_cvt_pk_bf16_f32 v146, v21, v146
	v_cvt_pk_bf16_f32 v147, v23, v147
	global_store_dwordx4 v26, v[144:147], s[46:47]
	v_lshlrev_b32_e32 v16, 16, v156
	v_and_b32_e32 v156, s48, v156
	v_lshlrev_b32_e32 v17, 16, v152
	v_and_b32_e32 v152, s48, v152
	v_lshlrev_b32_e32 v18, 16, v157
	v_and_b32_e32 v157, s48, v157
	v_lshlrev_b32_e32 v19, 16, v153
	v_and_b32_e32 v153, s48, v153
	v_lshlrev_b32_e32 v20, 16, v158
	v_and_b32_e32 v158, s48, v158
	v_lshlrev_b32_e32 v21, 16, v154
	v_and_b32_e32 v154, s48, v154
	v_lshlrev_b32_e32 v22, 16, v159
	v_and_b32_e32 v159, s48, v159
	v_lshlrev_b32_e32 v23, 16, v155
	v_and_b32_e32 v155, s48, v155
	v_mul_f32_e32 v16, v24, v16
	v_mul_f32_e32 v156, v24, v156
	v_mul_f32_e32 v18, v24, v18
	v_mul_f32_e32 v157, v24, v157
	v_mul_f32_e32 v20, v24, v20
	v_mul_f32_e32 v158, v24, v158
	v_mul_f32_e32 v22, v24, v22
	v_mul_f32_e32 v159, v24, v159
	v_fmac_f32_e32 v17, v0, v16
	v_fmac_f32_e32 v152, v1, v156
	v_fmac_f32_e32 v19, v2, v18
	v_fmac_f32_e32 v153, v3, v157
	v_fmac_f32_e32 v21, v4, v20
	v_fmac_f32_e32 v154, v5, v158
	v_fmac_f32_e32 v23, v6, v22
	v_fmac_f32_e32 v155, v7, v159
	v_cvt_pk_bf16_f32 v152, v17, v152
	v_cvt_pk_bf16_f32 v153, v19, v153
	v_cvt_pk_bf16_f32 v154, v21, v154
	v_cvt_pk_bf16_f32 v155, v23, v155
	global_store_dwordx4 v26, v[152:155], s[46:47] offset:1024
	s_mov_b64 s[96:97], 0
	s_branch .LBB0_92
.Lx1_generic:
	v_mov_b32_e32 v0, v208
	v_readlane_b32 s3, v254, 55
	v_ashrrev_i32_e32 v1, 6, v0
	s_mov_b32 s1, s54
	v_add_u32_e32 v16, s3, v1
	v_cmp_gt_i32_e32 vcc, s71, v16
	s_and_saveexec_b64 s[4:5], vcc
	s_cbranch_execz .LBB0_91
	s_load_dwordx2 s[8:9], s[36:37], 0x18
	s_lshl_b32 s10, s94, 10
	s_ashr_i32 s11, s10, 31
	s_lshl_b32 s6, s1, 3
	s_lshl_b64 s[10:11], s[10:11], 2
	v_and_b32_e32 v22, 63, v0
	s_waitcnt lgkmcnt(0)
	s_add_u32 s8, s8, s10
	s_addc_u32 s9, s9, s11
	v_lshlrev_b32_e32 v12, 5, v22
	global_load_dwordx4 v[0:3], v12, s[8:9] offset:2048
	global_load_dwordx4 v[4:7], v12, s[8:9] offset:2064
	global_load_dwordx4 v[8:11], v12, s[8:9]
	s_nop 0
	global_load_dwordx4 v[12:15], v12, s[8:9] offset:16
	v_ashrrev_i32_e32 v17, 31, v16
	s_ashr_i32 s7, s6, 31
	v_lshlrev_b64 v[20:21], 11, v[16:17]
	v_cmp_eq_u32_e64 s[40:41], 0, v22
	v_lshlrev_b64 v[18:19], 2, v[16:17]
	s_lshl_b64 s[8:9], s[6:7], 2
	v_lshl_or_b32 v20, v22, 4, v20
	s_lshl_b64 s[10:11], s[6:7], 11
	s_mov_b64 s[12:13], 0
	s_branch .LBB0_89

; __device__ void phase_x1(KP P, int layer) {
;     ...
;     for (int row = gw; row < MTOK; row += nw) {
;         const float rstd = rsqrtf(ssq2[row] * (1.f / 1024.f) + EPS);
;         if (lane == 0) ssq[row] = 0.f;
.LBB0_89:
	v_lshl_add_u64 v[22:23], s[90:91], 0, v[18:19]
	v_add_co_u32_e32 v24, vcc, 0x8900000, v22
	s_nop 1
	v_addc_co_u32_e32 v25, vcc, 0, v23, vcc
	global_load_dword v17, v[24:25], off
	v_add_co_u32_e32 v24, vcc, 0x20000, v24
	s_nop 1
	v_addc_co_u32_e32 v25, vcc, 0, v25, vcc
	global_load_dword v44, v[24:25], off
	v_add_co_u32_e32 v24, vcc, 0x20000, v24
	s_nop 1
	v_addc_co_u32_e32 v25, vcc, 0, v25, vcc
	global_load_dword v45, v[24:25], off
	v_add_co_u32_e32 v24, vcc, 0x20000, v24
	s_nop 1
	v_addc_co_u32_e32 v25, vcc, 0, v25, vcc
	global_load_dword v46, v[24:25], off
	v_add_co_u32_e32 v24, vcc, 0x20000, v24
	s_nop 1
	v_addc_co_u32_e32 v25, vcc, 0, v25, vcc
	global_load_dword v47, v[24:25], off
	v_add_co_u32_e32 v24, vcc, 0x20000, v24
	s_nop 1
	v_addc_co_u32_e32 v25, vcc, 0, v25, vcc
	global_load_dword v48, v[24:25], off
	v_add_co_u32_e32 v24, vcc, 0x20000, v24
	s_nop 1
	v_addc_co_u32_e32 v25, vcc, 0, v25, vcc
	global_load_dword v49, v[24:25], off
	v_add_co_u32_e32 v24, vcc, 0x20000, v24
	s_nop 1
	v_addc_co_u32_e32 v25, vcc, 0, v25, vcc
	global_load_dword v50, v[24:25], off
	v_add_co_u32_e32 v24, vcc, 0x20000, v24
	s_nop 1
	v_addc_co_u32_e32 v25, vcc, 0, v25, vcc
	global_load_dword v51, v[24:25], off
	v_add_co_u32_e32 v24, vcc, 0x20000, v24
	s_nop 1
	v_addc_co_u32_e32 v25, vcc, 0, v25, vcc
	global_load_dword v52, v[24:25], off
	v_add_co_u32_e32 v24, vcc, 0x20000, v24
	s_nop 1
	v_addc_co_u32_e32 v25, vcc, 0, v25, vcc
	global_load_dword v53, v[24:25], off
	v_add_co_u32_e32 v24, vcc, 0x20000, v24
	s_nop 1
	v_addc_co_u32_e32 v25, vcc, 0, v25, vcc
	global_load_dword v54, v[24:25], off
	v_add_co_u32_e32 v24, vcc, 0x20000, v24
	s_nop 1
	v_addc_co_u32_e32 v25, vcc, 0, v25, vcc
	global_load_dword v55, v[24:25], off
	v_add_co_u32_e32 v24, vcc, 0x20000, v24
	s_nop 1
	v_addc_co_u32_e32 v25, vcc, 0, v25, vcc
	global_load_dword v56, v[24:25], off
	v_add_co_u32_e32 v24, vcc, 0x20000, v24
	s_nop 1
	v_addc_co_u32_e32 v25, vcc, 0, v25, vcc
	global_load_dword v57, v[24:25], off
	v_add_co_u32_e32 v24, vcc, 0x20000, v24
	s_nop 1
	v_addc_co_u32_e32 v25, vcc, 0, v25, vcc
	global_load_dword v58, v[24:25], off
	s_waitcnt vmcnt(0)
	v_add_f32_e32 v17, v17, v44
	v_add_f32_e32 v17, v17, v45
	v_add_f32_e32 v17, v17, v46
	v_add_f32_e32 v17, v17, v47
	v_add_f32_e32 v17, v17, v48
	v_add_f32_e32 v17, v17, v49
	v_add_f32_e32 v17, v17, v50
	v_add_f32_e32 v17, v17, v51
	v_add_f32_e32 v17, v17, v52
	v_add_f32_e32 v17, v17, v53
	v_add_f32_e32 v17, v17, v54
	v_add_f32_e32 v17, v17, v55
	v_add_f32_e32 v17, v17, v56
	v_add_f32_e32 v17, v17, v57
	v_add_f32_e32 v17, v17, v58
	s_and_saveexec_b64 s[14:15], s[40:41]
	s_cbranch_execz .LBB0_88
	v_add_co_u32_e32 v22, vcc, 0x8700000, v22
	s_nop 1
	v_addc_co_u32_e32 v23, vcc, 0, v23, vcc
	global_store_dword v[22:23], v169, off
	s_branch .LBB0_88

;     __device__ __forceinline__ void operator()(const f32x4 (&acc)[2][2][4][2], const Unit& u, int wr, int wc, int fr, int fq, const LAS float* rsl) const {
;     ...
;                     for (int j = 0; j < 4; ++j) { float sa, sb; sigmoid2(g0[j], g1[j], sa, sb); x0[j] += sa * pv[j]; x1[j] += sb * pv[4 + j]; s += x0[j] * x0[j] + x1[j] * x1[j]; }
;                     if (xb) store8bf(xb + off, x0, x1);
;                     else { *(f32x4*)(X + off) = x0; *(f32x4*)(X + off + 4) = x1; } }
;                 if (xb) { s += __shfl_xor(s, 16); s += __shfl_xor(s, 32); if (fq == 0) atomicAdd(ssq + row, s); }
.LBB0_130:
	v_pk_mul_f32 v[144:145], v[156:157], v[156:157]
	v_pk_mul_f32 v[146:147], v[158:159], v[158:159]
	v_pk_fma_f32 v[144:145], v[152:153], v[152:153], v[144:145]
	v_pk_fma_f32 v[146:147], v[154:155], v[154:155], v[146:147]
	v_add_f32_e32 v144, v144, v145
	v_pk_mul_f32 v[148:149], v[164:165], v[164:165]
	v_add_f32_e32 v144, v146, v144
	v_pk_fma_f32 v[148:149], v[160:161], v[160:161], v[148:149]
	v_add_f32_e32 v144, v147, v144
	v_pk_mul_f32 v[150:151], v[166:167], v[166:167]
	v_add_f32_e32 v144, v148, v144
	v_pk_fma_f32 v[150:151], v[162:163], v[162:163], v[150:151]
	v_add_f32_e32 v144, v149, v144
	v_cmp_lt_i32_e32 vcc, v214, v215
	v_add_f32_e32 v144, v150, v144
	v_add_f32_e32 v144, v151, v144
	v_cndmask_b32_e32 v145, v212, v214, vcc
	v_lshlrev_b32_e32 v145, 2, v145
	ds_bpermute_b32 v145, v145, v144
	v_cmp_lt_i32_e32 vcc, v216, v215
	s_waitcnt lgkmcnt(0)
	v_add_f32_e32 v144, v144, v145
	v_cndmask_b32_e32 v145, v212, v216, vcc
	v_lshlrev_b32_e32 v145, 2, v145
	ds_bpermute_b32 v145, v145, v144
	s_and_saveexec_b64 s[36:37], s[40:41]
	s_cbranch_execz .LBB0_132
	s_bfe_u32 vcc_lo, s79, 0x20006
	s_lshl2_add_u32 vcc_lo, s48, vcc_lo
	s_lshl_b32 vcc_lo, vcc_lo, 17
	s_add_u32 vcc_lo, s62, vcc_lo
	s_addc_u32 vcc_hi, s63, 0
	v_lshl_add_u64 v[146:147], v[192:193], 2, vcc
	s_waitcnt lgkmcnt(0)
	v_add_f32_e32 v144, v144, v145
	global_store_dword v[146:147], v144, off

;     __device__ __forceinline__ void operator()(const f32x4 (&acc)[2][2][4][2], const Unit& u, int wr, int wc, int fr, int fq, const LAS float* rsl) const {
;     ...
;                     for (int j = 0; j < 4; ++j) { float sa, sb; sigmoid2(g0[j], g1[j], sa, sb); x0[j] += sa * pv[j]; x1[j] += sb * pv[4 + j]; s += x0[j] * x0[j] + x1[j] * x1[j]; }
;                     if (xb) store8bf(xb + off, x0, x1);
;                     else { *(f32x4*)(X + off) = x0; *(f32x4*)(X + off + 4) = x1; } }
;                 if (xb) { s += __shfl_xor(s, 16); s += __shfl_xor(s, 32); if (fq == 0) atomicAdd(ssq + row, s); }
.LBB0_142:
	v_pk_mul_f32 v[128:129], v[164:165], v[164:165]
	v_pk_mul_f32 v[130:131], v[166:167], v[166:167]
	v_pk_fma_f32 v[128:129], v[160:161], v[160:161], v[128:129]
	v_pk_fma_f32 v[130:131], v[162:163], v[162:163], v[130:131]
	v_add_f32_e32 v128, v128, v129
	v_pk_mul_f32 v[132:133], v[140:141], v[140:141]
	v_add_f32_e32 v128, v130, v128
	v_pk_fma_f32 v[132:133], v[136:137], v[136:137], v[132:133]
	v_add_f32_e32 v128, v131, v128
	v_pk_mul_f32 v[134:135], v[142:143], v[142:143]
	v_add_f32_e32 v128, v132, v128
	v_pk_fma_f32 v[134:135], v[138:139], v[138:139], v[134:135]
	v_add_f32_e32 v128, v133, v128
	v_cmp_lt_i32_e32 vcc, v214, v215
	v_add_f32_e32 v128, v134, v128
	v_add_f32_e32 v128, v135, v128
	v_cndmask_b32_e32 v129, v212, v214, vcc
	v_lshlrev_b32_e32 v129, 2, v129
	ds_bpermute_b32 v129, v129, v128
	v_cmp_lt_i32_e32 vcc, v216, v215
	s_waitcnt lgkmcnt(0)
	v_add_f32_e32 v128, v128, v129
	v_cndmask_b32_e32 v129, v212, v216, vcc
	v_lshlrev_b32_e32 v129, 2, v129
	ds_bpermute_b32 v129, v129, v128
	s_and_saveexec_b64 s[36:37], s[40:41]
	s_cbranch_execz .LBB0_144
	s_bfe_u32 vcc_lo, s79, 0x20006
	s_lshl2_add_u32 vcc_lo, s48, vcc_lo
	s_lshl_b32 vcc_lo, vcc_lo, 17
	s_add_u32 vcc_lo, s62, vcc_lo
	s_addc_u32 vcc_hi, s63, 0
	v_lshl_add_u64 v[130:131], v[194:195], 2, vcc
	s_waitcnt lgkmcnt(0)
	v_add_f32_e32 v128, v128, v129
	global_store_dword v[130:131], v128, off

;     __device__ __forceinline__ void operator()(const f32x4 (&acc)[2][2][4][2], const Unit& u, int wr, int wc, int fr, int fq, const LAS float* rsl) const {
;     ...
;                     for (int j = 0; j < 4; ++j) { float sa, sb; sigmoid2(g0[j], g1[j], sa, sb); x0[j] += sa * pv[j]; x1[j] += sb * pv[4 + j]; s += x0[j] * x0[j] + x1[j] * x1[j]; }
;                     if (xb) store8bf(xb + off, x0, x1);
;                     else { *(f32x4*)(X + off) = x0; *(f32x4*)(X + off + 4) = x1; } }
;                 if (xb) { s += __shfl_xor(s, 16); s += __shfl_xor(s, 32); if (fq == 0) atomicAdd(ssq + row, s); }
.LBB0_154:
	v_pk_mul_f32 v[144:145], v[164:165], v[164:165]
	v_pk_mul_f32 v[146:147], v[158:159], v[158:159]
	v_pk_fma_f32 v[132:133], v[132:133], v[132:133], v[144:145]
	v_pk_mul_f32 v[144:145], v[166:167], v[166:167]
	v_add_f32_e32 v132, v132, v133
	v_pk_fma_f32 v[134:135], v[134:135], v[134:135], v[144:145]
	v_pk_mul_f32 v[144:145], v[156:157], v[156:157]
	v_add_f32_e32 v132, v134, v132
	v_pk_fma_f32 v[144:145], v[152:153], v[152:153], v[144:145]
	v_add_f32_e32 v132, v135, v132
	v_add_f32_e32 v132, v144, v132
	v_pk_fma_f32 v[146:147], v[154:155], v[154:155], v[146:147]
	v_add_f32_e32 v132, v145, v132
	v_cmp_lt_i32_e32 vcc, v214, v215
	v_add_f32_e32 v132, v146, v132
	v_add_f32_e32 v132, v147, v132
	v_cndmask_b32_e32 v133, v212, v214, vcc
	v_lshlrev_b32_e32 v133, 2, v133
	ds_bpermute_b32 v133, v133, v132
	v_cmp_lt_i32_e32 vcc, v216, v215
	s_waitcnt lgkmcnt(0)
	v_add_f32_e32 v132, v132, v133
	v_cndmask_b32_e32 v133, v212, v216, vcc
	v_lshlrev_b32_e32 v133, 2, v133
	ds_bpermute_b32 v133, v133, v132
	s_and_saveexec_b64 s[36:37], s[40:41]
	s_cbranch_execz .LBB0_156
	s_bfe_u32 vcc_lo, s79, 0x20006
	s_lshl2_add_u32 vcc_lo, s48, vcc_lo
	s_lshl_b32 vcc_lo, vcc_lo, 17
	s_add_u32 vcc_lo, s62, vcc_lo
	s_addc_u32 vcc_hi, s63, 0
	v_lshl_add_u64 v[134:135], v[200:201], 2, vcc
	s_waitcnt lgkmcnt(0)
	v_add_f32_e32 v132, v132, v133
	global_store_dword v[134:135], v132, off

;     __device__ __forceinline__ void operator()(const f32x4 (&acc)[2][2][4][2], const Unit& u, int wr, int wc, int fr, int fq, const LAS float* rsl) const {
;     ...
;                     for (int j = 0; j < 4; ++j) { float sa, sb; sigmoid2(g0[j], g1[j], sa, sb); x0[j] += sa * pv[j]; x1[j] += sb * pv[4 + j]; s += x0[j] * x0[j] + x1[j] * x1[j]; }
;                     if (xb) store8bf(xb + off, x0, x1);
;                     else { *(f32x4*)(X + off) = x0; *(f32x4*)(X + off + 4) = x1; } }
;                 if (xb) { s += __shfl_xor(s, 16); s += __shfl_xor(s, 32); if (fq == 0) atomicAdd(ssq + row, s); }
.LBB0_166:
	v_pk_mul_f32 v[128:129], v[156:157], v[156:157]
	v_pk_mul_f32 v[130:131], v[158:159], v[158:159]
	v_pk_fma_f32 v[128:129], v[152:153], v[152:153], v[128:129]
	v_pk_fma_f32 v[130:131], v[154:155], v[154:155], v[130:131]
	v_add_f32_e32 v128, v128, v129
	v_pk_mul_f32 v[136:137], v[160:161], v[160:161]
	v_add_f32_e32 v128, v130, v128
	v_pk_fma_f32 v[136:137], v[140:141], v[140:141], v[136:137]
	v_add_f32_e32 v128, v131, v128
	v_pk_mul_f32 v[138:139], v[162:163], v[162:163]
	v_add_f32_e32 v128, v136, v128
	v_pk_fma_f32 v[138:139], v[142:143], v[142:143], v[138:139]
	v_add_f32_e32 v128, v137, v128
	v_cmp_lt_i32_e32 vcc, v214, v215
	v_add_f32_e32 v128, v138, v128
	v_add_f32_e32 v128, v139, v128
	v_cndmask_b32_e32 v129, v212, v214, vcc
	v_lshlrev_b32_e32 v129, 2, v129
	ds_bpermute_b32 v129, v129, v128
	v_cmp_lt_i32_e32 vcc, v216, v215
	s_waitcnt lgkmcnt(0)
	v_add_f32_e32 v128, v128, v129
	v_cndmask_b32_e32 v129, v212, v216, vcc
	v_lshlrev_b32_e32 v129, 2, v129
	ds_bpermute_b32 v129, v129, v128
	s_and_saveexec_b64 s[36:37], s[40:41]
	s_cbranch_execz .LBB0_168
	s_bfe_u32 vcc_lo, s79, 0x20006
	s_lshl2_add_u32 vcc_lo, s48, vcc_lo
	s_lshl_b32 vcc_lo, vcc_lo, 17
	s_add_u32 vcc_lo, s62, vcc_lo
	s_addc_u32 vcc_hi, s63, 0
	v_lshl_add_u64 v[130:131], v[196:197], 2, vcc
	s_waitcnt lgkmcnt(0)
	v_add_f32_e32 v128, v128, v129
	global_store_dword v[130:131], v128, off

;     __device__ __forceinline__ void operator()(const f32x4 (&acc)[2][2][4][2], const Unit& u, int wr, int wc, int fr, int fq, const LAS float* rsl) const {
;     ...
;                     for (int j = 0; j < 4; ++j) { float sa, sb; sigmoid2(g0[j], g1[j], sa, sb); x0[j] += sa * pv[j]; x1[j] += sb * pv[4 + j]; s += x0[j] * x0[j] + x1[j] * x1[j]; }
;                     if (xb) store8bf(xb + off, x0, x1);
;                     else { *(f32x4*)(X + off) = x0; *(f32x4*)(X + off + 4) = x1; } }
;                 if (xb) { s += __shfl_xor(s, 16); s += __shfl_xor(s, 32); if (fq == 0) atomicAdd(ssq + row, s); }
.LBB0_178:
	v_pk_mul_f32 v[132:133], v[160:161], v[160:161]
	v_pk_mul_f32 v[134:135], v[166:167], v[166:167]
	v_pk_fma_f32 v[128:129], v[128:129], v[128:129], v[132:133]
	v_pk_mul_f32 v[132:133], v[162:163], v[162:163]
	v_add_f32_e32 v128, v128, v129
	v_pk_fma_f32 v[130:131], v[130:131], v[130:131], v[132:133]
	v_pk_mul_f32 v[132:133], v[164:165], v[164:165]
	v_add_f32_e32 v128, v130, v128
	v_pk_fma_f32 v[132:133], v[148:149], v[148:149], v[132:133]
	v_add_f32_e32 v128, v131, v128
	v_add_f32_e32 v128, v132, v128
	v_pk_fma_f32 v[134:135], v[150:151], v[150:151], v[134:135]
	v_add_f32_e32 v128, v133, v128
	v_cmp_lt_i32_e32 vcc, v214, v215
	v_add_f32_e32 v128, v134, v128
	v_add_f32_e32 v128, v135, v128
	v_cndmask_b32_e32 v129, v212, v214, vcc
	v_lshlrev_b32_e32 v129, 2, v129
	ds_bpermute_b32 v129, v129, v128
	v_cmp_lt_i32_e32 vcc, v216, v215
	s_waitcnt lgkmcnt(0)
	v_add_f32_e32 v128, v128, v129
	v_cndmask_b32_e32 v129, v212, v216, vcc
	v_lshlrev_b32_e32 v129, 2, v129
	ds_bpermute_b32 v129, v129, v128
	s_and_saveexec_b64 s[36:37], s[40:41]
	s_cbranch_execz .LBB0_180
	s_bfe_u32 vcc_lo, s79, 0x20006
	s_lshl2_add_u32 vcc_lo, s48, vcc_lo
	s_lshl_b32 vcc_lo, vcc_lo, 17
	s_add_u32 vcc_lo, s62, vcc_lo
	s_addc_u32 vcc_hi, s63, 0
	v_lshl_add_u64 v[130:131], v[194:195], 2, vcc
	s_waitcnt lgkmcnt(0)
	v_add_f32_e32 v128, v128, v129
	global_store_dword v[130:131], v128, off

;     __device__ __forceinline__ void operator()(const f32x4 (&acc)[2][2][4][2], const Unit& u, int wr, int wc, int fr, int fq, const LAS float* rsl) const {
;     ...
;                     for (int j = 0; j < 4; ++j) { float sa, sb; sigmoid2(g0[j], g1[j], sa, sb); x0[j] += sa * pv[j]; x1[j] += sb * pv[4 + j]; s += x0[j] * x0[j] + x1[j] * x1[j]; }
;                     if (xb) store8bf(xb + off, x0, x1);
;                     else { *(f32x4*)(X + off) = x0; *(f32x4*)(X + off + 4) = x1; } }
;                 if (xb) { s += __shfl_xor(s, 16); s += __shfl_xor(s, 32); if (fq == 0) atomicAdd(ssq + row, s); }
.LBB0_190:
	v_pk_mul_f32 v[136:137], v[164:165], v[164:165]
	v_pk_mul_f32 v[138:139], v[166:167], v[166:167]
	v_pk_fma_f32 v[136:137], v[160:161], v[160:161], v[136:137]
	v_pk_fma_f32 v[138:139], v[162:163], v[162:163], v[138:139]
	v_add_f32_e32 v136, v136, v137
	v_pk_mul_f32 v[140:141], v[156:157], v[156:157]
	v_add_f32_e32 v136, v138, v136
	v_pk_fma_f32 v[140:141], v[152:153], v[152:153], v[140:141]
	v_add_f32_e32 v136, v139, v136
	v_pk_mul_f32 v[142:143], v[158:159], v[158:159]
	v_add_f32_e32 v136, v140, v136
	v_pk_fma_f32 v[142:143], v[154:155], v[154:155], v[142:143]
	v_add_f32_e32 v136, v141, v136
	v_cmp_lt_i32_e32 vcc, v214, v215
	v_add_f32_e32 v136, v142, v136
	v_add_f32_e32 v136, v143, v136
	v_cndmask_b32_e32 v137, v212, v214, vcc
	v_lshlrev_b32_e32 v137, 2, v137
	ds_bpermute_b32 v137, v137, v136
	v_cmp_lt_i32_e32 vcc, v216, v215
	s_waitcnt lgkmcnt(0)
	v_add_f32_e32 v136, v136, v137
	v_cndmask_b32_e32 v137, v212, v216, vcc
	v_lshlrev_b32_e32 v137, 2, v137
	ds_bpermute_b32 v137, v137, v136
	s_and_saveexec_b64 s[36:37], s[40:41]
	s_cbranch_execz .LBB0_192
	s_bfe_u32 vcc_lo, s79, 0x20006
	s_lshl2_add_u32 vcc_lo, s48, vcc_lo
	s_lshl_b32 vcc_lo, vcc_lo, 17
	s_add_u32 vcc_lo, s62, vcc_lo
	s_addc_u32 vcc_hi, s63, 0
	v_lshl_add_u64 v[138:139], v[196:197], 2, vcc
	s_waitcnt lgkmcnt(0)
	v_add_f32_e32 v136, v136, v137
	global_store_dword v[138:139], v136, off

;     __device__ __forceinline__ void operator()(const f32x4 (&acc)[2][2][4][2], const Unit& u, int wr, int wc, int fr, int fq, const LAS float* rsl) const {
;     ...
;                     for (int j = 0; j < 4; ++j) { float sa, sb; sigmoid2(g0[j], g1[j], sa, sb); x0[j] += sa * pv[j]; x1[j] += sb * pv[4 + j]; s += x0[j] * x0[j] + x1[j] * x1[j]; }
;                     if (xb) store8bf(xb + off, x0, x1);
;                     else { *(f32x4*)(X + off) = x0; *(f32x4*)(X + off + 4) = x1; } }
;                 if (xb) { s += __shfl_xor(s, 16); s += __shfl_xor(s, 32); if (fq == 0) atomicAdd(ssq + row, s); }
.LBB0_202:
	v_pk_mul_f32 v[128:129], v[164:165], v[164:165]
	v_pk_mul_f32 v[130:131], v[166:167], v[166:167]
	v_pk_fma_f32 v[128:129], v[160:161], v[160:161], v[128:129]
	v_pk_fma_f32 v[130:131], v[162:163], v[162:163], v[130:131]
	v_add_f32_e32 v128, v128, v129
	v_pk_mul_f32 v[132:133], v[148:149], v[148:149]
	v_add_f32_e32 v128, v130, v128
	v_pk_fma_f32 v[132:133], v[144:145], v[144:145], v[132:133]
	v_add_f32_e32 v128, v131, v128
	v_pk_mul_f32 v[134:135], v[150:151], v[150:151]
	v_add_f32_e32 v128, v132, v128
	v_pk_fma_f32 v[134:135], v[146:147], v[146:147], v[134:135]
	v_add_f32_e32 v128, v133, v128
	v_cmp_lt_i32_e32 vcc, v214, v215
	v_add_f32_e32 v128, v134, v128
	v_add_f32_e32 v128, v135, v128
	v_cndmask_b32_e32 v129, v212, v214, vcc
	v_lshlrev_b32_e32 v129, 2, v129
	ds_bpermute_b32 v129, v129, v128
	v_cmp_lt_i32_e32 vcc, v216, v215
	s_waitcnt lgkmcnt(0)
	v_add_f32_e32 v128, v128, v129
	v_cndmask_b32_e32 v129, v212, v216, vcc
	v_lshlrev_b32_e32 v129, 2, v129
	ds_bpermute_b32 v129, v129, v128
	s_and_saveexec_b64 s[36:37], s[40:41]
	s_cbranch_execz .LBB0_204
	s_bfe_u32 vcc_lo, s79, 0x20006
	s_lshl2_add_u32 vcc_lo, s48, vcc_lo
	s_lshl_b32 vcc_lo, vcc_lo, 17
	s_add_u32 vcc_lo, s62, vcc_lo
	s_addc_u32 vcc_hi, s63, 0
	v_lshl_add_u64 v[130:131], v[196:197], 2, vcc
	s_waitcnt lgkmcnt(0)
	v_add_f32_e32 v128, v128, v129
	global_store_dword v[130:131], v128, off

;     __device__ __forceinline__ void operator()(const f32x4 (&acc)[2][2][4][2], const Unit& u, int wr, int wc, int fr, int fq, const LAS float* rsl) const {
;     ...
;                     for (int j = 0; j < 4; ++j) { float sa, sb; sigmoid2(g0[j], g1[j], sa, sb); x0[j] += sa * pv[j]; x1[j] += sb * pv[4 + j]; s += x0[j] * x0[j] + x1[j] * x1[j]; }
;                     if (xb) store8bf(xb + off, x0, x1);
;                     else { *(f32x4*)(X + off) = x0; *(f32x4*)(X + off + 4) = x1; } }
;                 if (xb) { s += __shfl_xor(s, 16); s += __shfl_xor(s, 32); if (fq == 0) atomicAdd(ssq + row, s); }
.LBB0_214:
	v_pk_mul_f32 v[132:133], v[132:133], v[132:133]
	v_cmp_lt_i32_e32 vcc, v214, v215
	v_pk_fma_f32 v[128:129], v[128:129], v[128:129], v[132:133]
	v_pk_mul_f32 v[132:133], v[134:135], v[134:135]
	v_add_f32_e32 v128, v128, v129
	v_pk_fma_f32 v[130:131], v[130:131], v[130:131], v[132:133]
	v_pk_mul_f32 v[132:133], v[148:149], v[148:149]
	v_add_f32_e32 v128, v130, v128
	v_pk_fma_f32 v[132:133], v[144:145], v[144:145], v[132:133]
	v_add_f32_e32 v128, v131, v128
	v_pk_mul_f32 v[134:135], v[150:151], v[150:151]
	v_add_f32_e32 v128, v132, v128
	v_pk_fma_f32 v[134:135], v[146:147], v[146:147], v[134:135]
	v_add_f32_e32 v128, v133, v128
	v_add_f32_e32 v128, v134, v128
	v_cndmask_b32_e32 v129, v212, v214, vcc
	v_add_f32_e32 v128, v135, v128
	v_lshlrev_b32_e32 v129, 2, v129
	ds_bpermute_b32 v129, v129, v128
	v_cmp_lt_i32_e32 vcc, v216, v215
	s_waitcnt lgkmcnt(0)
	v_add_f32_e32 v128, v128, v129
	v_cndmask_b32_e32 v129, v212, v216, vcc
	v_lshlrev_b32_e32 v129, 2, v129
	ds_bpermute_b32 v129, v129, v128
	s_and_saveexec_b64 s[36:37], s[40:41]
	s_cbranch_execz .LBB0_216
	s_bfe_u32 vcc_lo, s79, 0x20006
	s_lshl2_add_u32 vcc_lo, s48, vcc_lo
	s_lshl_b32 vcc_lo, vcc_lo, 17
	s_add_u32 vcc_lo, s62, vcc_lo
	s_addc_u32 vcc_hi, s63, 0
	v_lshl_add_u64 v[130:131], v[160:161], 2, vcc
	s_waitcnt lgkmcnt(0)
	v_add_f32_e32 v128, v128, v129
	global_store_dword v[130:131], v128, off

;     __device__ __forceinline__ void operator()(const f32x4 (&acc)[2][2][4][2], const Unit& u, int wr, int wc, int fr, int fq, const LAS float* rsl) const {
;     ...
;             for (int m = 0; m < 4; ++m) { const int row = row0 + ai * 128 + m * 16; bf16_t* rp = O + (size_t)row * 1024 + col0; float s = 0.f;
; #pragma unroll
;                 for (int bj = 0; bj < 2; ++bj) { const f32x4 v0 = acc[ai][bj][m][0], v1 = acc[ai][bj][m][1]; store8bf(rp + bj * 128, v0, v1);
; #pragma unroll
;                     for (int j = 0; j < 4; ++j) s += v0[j] * v0[j] + v1[j] * v1[j]; }
;                 s += __shfl_xor(s, 16); s += __shfl_xor(s, 32);
;                 if (fq == 0) atomicAdd(ssq + row, s);
;                 if (m & 1) asm volatile("" ::: "memory"); }
.LBB0_218:
	s_and_b64 vcc, exec, s[36:37]
	s_cbranch_vccz .LBB0_236
	v_add_u32_e32 v130, s34, v171
	v_lshl_or_b32 v128, s48, 8, v227
	s_waitcnt lgkmcnt(0)
	v_ashrrev_i32_e32 v129, 31, v128
	v_ashrrev_i32_e32 v131, 31, v130
	v_lshl_add_u64 v[128:129], v[128:129], 1, s[8:9]
	v_lshlrev_b64 v[132:133], 11, v[130:131]
	v_lshl_add_u64 v[136:137], v[128:129], 0, v[132:133]
	v_cvt_pk_bf16_f32 v132, v124, v125
	v_cvt_pk_bf16_f32 v133, v126, v127
	v_cvt_pk_bf16_f32 v134, v120, v121
	v_cvt_pk_bf16_f32 v135, v122, v123
	global_store_dwordx4 v[136:137], v[132:135], off
	v_cmp_lt_i32_e32 vcc, v214, v215
	s_nop 0
	v_mul_f32_e32 v132, v120, v120
	v_mul_f32_e32 v133, v121, v121
	v_fmac_f32_e32 v132, v124, v124
	v_fmac_f32_e32 v133, v125, v125
	v_add_f32_e32 v132, v132, v133
	v_mul_f32_e32 v133, v122, v122
	v_fmac_f32_e32 v133, v126, v126
	v_add_f32_e32 v132, v133, v132
	v_mul_f32_e32 v133, v123, v123
	v_fmac_f32_e32 v133, v127, v127
	v_add_f32_e32 v138, v133, v132
	v_cvt_pk_bf16_f32 v132, v116, v117
	v_cvt_pk_bf16_f32 v133, v118, v119
	v_cvt_pk_bf16_f32 v134, v108, v109
	v_cvt_pk_bf16_f32 v135, v110, v111
	global_store_dwordx4 v[136:137], v[132:135], off offset:256
	s_nop 1
	v_mul_f32_e32 v132, v108, v108
	v_fmac_f32_e32 v132, v116, v116
	v_mul_f32_e32 v133, v109, v109
	v_add_f32_e32 v132, v138, v132
	v_fmac_f32_e32 v133, v117, v117
	v_add_f32_e32 v132, v133, v132
	v_mul_f32_e32 v133, v110, v110
	v_fmac_f32_e32 v133, v118, v118
	v_add_f32_e32 v132, v133, v132
	v_mul_f32_e32 v133, v111, v111
	v_fmac_f32_e32 v133, v119, v119
	v_add_f32_e32 v132, v133, v132
	v_cndmask_b32_e32 v133, v212, v214, vcc
	v_lshlrev_b32_e32 v134, 2, v133
	ds_bpermute_b32 v133, v134, v132
	v_cmp_lt_i32_e32 vcc, v216, v215
	s_waitcnt lgkmcnt(0)
	v_add_f32_e32 v132, v132, v133
	v_cndmask_b32_e32 v133, v212, v216, vcc
	v_lshlrev_b32_e32 v135, 2, v133
	ds_bpermute_b32 v133, v135, v132
	s_and_saveexec_b64 s[36:37], s[40:41]
	s_cbranch_execz .LBB0_221
	s_waitcnt lgkmcnt(0)
	v_add_f32_e32 v136, v132, v133
	s_bfe_u32 vcc_lo, s79, 0x20006
	s_lshl2_add_u32 vcc_lo, s48, vcc_lo
	s_lshl_b32 vcc_lo, vcc_lo, 17
	s_add_u32 vcc_lo, s4, vcc_lo
	s_addc_u32 vcc_hi, s5, 0
	v_lshl_add_u64 v[132:133], v[130:131], 2, vcc
	global_store_dword v[132:133], v136, off
.LBB0_221:
	s_or_b64 exec, exec, s[36:37]
	v_or_b32_e32 v132, 16, v130
	s_waitcnt lgkmcnt(0)
	v_ashrrev_i32_e32 v133, 31, v132
	v_lshlrev_b64 v[136:137], 11, v[132:133]
	v_lshl_add_u64 v[140:141], v[128:129], 0, v[136:137]
	v_cvt_pk_bf16_f32 v136, v112, v113
	v_cvt_pk_bf16_f32 v137, v114, v115
	v_cvt_pk_bf16_f32 v138, v104, v105
	v_cvt_pk_bf16_f32 v139, v106, v107
	global_store_dwordx4 v[140:141], v[136:139], off
	v_mul_f32_e32 v131, v104, v104
	v_fmac_f32_e32 v131, v112, v112
	v_mul_f32_e32 v136, v105, v105
	v_fmac_f32_e32 v136, v113, v113
	v_add_f32_e32 v131, v131, v136
	v_mul_f32_e32 v136, v106, v106
	v_fmac_f32_e32 v136, v114, v114
	v_add_f32_e32 v131, v136, v131
	v_mul_f32_e32 v136, v107, v107
	v_fmac_f32_e32 v136, v115, v115
	v_add_f32_e32 v131, v136, v131
	v_cvt_pk_bf16_f32 v136, v100, v101
	v_cvt_pk_bf16_f32 v137, v102, v103
	v_cvt_pk_bf16_f32 v138, v92, v93
	v_cvt_pk_bf16_f32 v139, v94, v95
	global_store_dwordx4 v[140:141], v[136:139], off offset:256
	s_nop 1
	v_mul_f32_e32 v136, v92, v92
	v_fmac_f32_e32 v136, v100, v100
	v_add_f32_e32 v131, v131, v136
	v_mul_f32_e32 v136, v93, v93
	v_fmac_f32_e32 v136, v101, v101
	v_add_f32_e32 v131, v136, v131
	v_mul_f32_e32 v136, v94, v94
	v_fmac_f32_e32 v136, v102, v102
	v_add_f32_e32 v131, v136, v131
	v_mul_f32_e32 v136, v95, v95
	v_fmac_f32_e32 v136, v103, v103
	v_add_f32_e32 v131, v136, v131
	ds_bpermute_b32 v136, v134, v131
	s_waitcnt lgkmcnt(0)
	v_add_f32_e32 v131, v131, v136
	ds_bpermute_b32 v136, v135, v131
	s_and_saveexec_b64 s[36:37], s[40:41]
	s_cbranch_execz .LBB0_223
	s_waitcnt lgkmcnt(0)
	v_add_f32_e32 v131, v131, v136
	s_bfe_u32 vcc_lo, s79, 0x20006
	s_lshl2_add_u32 vcc_lo, s48, vcc_lo
	s_lshl_b32 vcc_lo, vcc_lo, 17
	s_add_u32 vcc_lo, s4, vcc_lo
	s_addc_u32 vcc_hi, s5, 0
	v_lshl_add_u64 v[132:133], v[132:133], 2, vcc
	global_store_dword v[132:133], v131, off
.LBB0_223:
	s_or_b64 exec, exec, s[36:37]
	v_or_b32_e32 v132, 32, v130
	v_ashrrev_i32_e32 v133, 31, v132
	s_waitcnt lgkmcnt(0)
	v_lshlrev_b64 v[136:137], 11, v[132:133]
	v_lshl_add_u64 v[140:141], v[128:129], 0, v[136:137]
	v_cvt_pk_bf16_f32 v136, v96, v97
	v_cvt_pk_bf16_f32 v137, v98, v99
	v_cvt_pk_bf16_f32 v138, v88, v89
	v_cvt_pk_bf16_f32 v139, v90, v91
	global_store_dwordx4 v[140:141], v[136:139], off
	v_mul_f32_e32 v131, v88, v88
	v_fmac_f32_e32 v131, v96, v96
	v_mul_f32_e32 v136, v89, v89
	v_fmac_f32_e32 v136, v97, v97
	v_add_f32_e32 v131, v131, v136
	v_mul_f32_e32 v136, v90, v90
	v_fmac_f32_e32 v136, v98, v98
	v_add_f32_e32 v131, v136, v131
	v_mul_f32_e32 v136, v91, v91
	v_fmac_f32_e32 v136, v99, v99
	v_add_f32_e32 v131, v136, v131
	v_cvt_pk_bf16_f32 v136, v84, v85
	v_cvt_pk_bf16_f32 v137, v86, v87
	v_cvt_pk_bf16_f32 v138, v76, v77
	v_cvt_pk_bf16_f32 v139, v78, v79
	global_store_dwordx4 v[140:141], v[136:139], off offset:256
	s_nop 1
	v_mul_f32_e32 v136, v76, v76
	v_fmac_f32_e32 v136, v84, v84
	v_add_f32_e32 v131, v131, v136
	v_mul_f32_e32 v136, v77, v77
	v_fmac_f32_e32 v136, v85, v85
	v_add_f32_e32 v131, v136, v131
	v_mul_f32_e32 v136, v78, v78
	v_fmac_f32_e32 v136, v86, v86
	v_add_f32_e32 v131, v136, v131
	v_mul_f32_e32 v136, v79, v79
	v_fmac_f32_e32 v136, v87, v87
	v_add_f32_e32 v131, v136, v131
	ds_bpermute_b32 v136, v134, v131
	s_waitcnt lgkmcnt(0)
	v_add_f32_e32 v131, v131, v136
	ds_bpermute_b32 v136, v135, v131
	s_and_saveexec_b64 s[36:37], s[40:41]
	s_cbranch_execz .LBB0_225
	s_waitcnt lgkmcnt(0)
	v_add_f32_e32 v131, v131, v136
	s_bfe_u32 vcc_lo, s79, 0x20006
	s_lshl2_add_u32 vcc_lo, s48, vcc_lo
	s_lshl_b32 vcc_lo, vcc_lo, 17
	s_add_u32 vcc_lo, s4, vcc_lo
	s_addc_u32 vcc_hi, s5, 0
	v_lshl_add_u64 v[132:133], v[132:133], 2, vcc
	global_store_dword v[132:133], v131, off
;     __device__ __forceinline__ void operator()(const f32x4 (&acc)[2][2][4][2], const Unit& u, int wr, int wc, int fr, int fq, const LAS float* rsl) const {
;     ...
;             for (int m = 0; m < 4; ++m) { const int row = row0 + ai * 128 + m * 16; bf16_t* rp = O + (size_t)row * 1024 + col0; float s = 0.f;
; #pragma unroll
;                 for (int bj = 0; bj < 2; ++bj) { const f32x4 v0 = acc[ai][bj][m][0], v1 = acc[ai][bj][m][1]; store8bf(rp + bj * 128, v0, v1);
; #pragma unroll
;                     for (int j = 0; j < 4; ++j) s += v0[j] * v0[j] + v1[j] * v1[j]; }
;                 s += __shfl_xor(s, 16); s += __shfl_xor(s, 32);
;                 if (fq == 0) atomicAdd(ssq + row, s);
;                 if (m & 1) asm volatile("" ::: "memory"); }
.LBB0_225:
	s_or_b64 exec, exec, s[36:37]
	v_or_b32_e32 v132, 48, v130
	v_ashrrev_i32_e32 v133, 31, v132
	s_waitcnt lgkmcnt(0)
	v_lshlrev_b64 v[136:137], 11, v[132:133]
	v_lshl_add_u64 v[140:141], v[128:129], 0, v[136:137]
	v_cvt_pk_bf16_f32 v136, v80, v81
	v_cvt_pk_bf16_f32 v137, v82, v83
	v_cvt_pk_bf16_f32 v138, v72, v73
	v_cvt_pk_bf16_f32 v139, v74, v75
	global_store_dwordx4 v[140:141], v[136:139], off
	v_mul_f32_e32 v131, v72, v72
	v_fmac_f32_e32 v131, v80, v80
	v_mul_f32_e32 v136, v73, v73
	v_fmac_f32_e32 v136, v81, v81
	v_add_f32_e32 v131, v131, v136
	v_mul_f32_e32 v136, v74, v74
	v_fmac_f32_e32 v136, v82, v82
	v_add_f32_e32 v131, v136, v131
	v_mul_f32_e32 v136, v75, v75
	v_fmac_f32_e32 v136, v83, v83
	v_add_f32_e32 v131, v136, v131
	v_cvt_pk_bf16_f32 v136, v68, v69
	v_cvt_pk_bf16_f32 v137, v70, v71
	v_cvt_pk_bf16_f32 v138, v64, v65
	v_cvt_pk_bf16_f32 v139, v66, v67
	global_store_dwordx4 v[140:141], v[136:139], off offset:256
	s_nop 1
	v_mul_f32_e32 v136, v64, v64
	v_fmac_f32_e32 v136, v68, v68
	v_add_f32_e32 v131, v131, v136
	v_mul_f32_e32 v136, v65, v65
	v_fmac_f32_e32 v136, v69, v69
	v_add_f32_e32 v131, v136, v131
	v_mul_f32_e32 v136, v66, v66
	v_fmac_f32_e32 v136, v70, v70
	v_add_f32_e32 v131, v136, v131
	v_mul_f32_e32 v136, v67, v67
	v_fmac_f32_e32 v136, v71, v71
	v_add_f32_e32 v131, v136, v131
	ds_bpermute_b32 v136, v134, v131
	s_waitcnt lgkmcnt(0)
	v_add_f32_e32 v131, v131, v136
	ds_bpermute_b32 v136, v135, v131
	s_and_saveexec_b64 s[36:37], s[40:41]
	s_cbranch_execz .LBB0_227
	s_waitcnt lgkmcnt(0)
	v_add_f32_e32 v131, v131, v136
	s_bfe_u32 vcc_lo, s79, 0x20006
	s_lshl2_add_u32 vcc_lo, s48, vcc_lo
	s_lshl_b32 vcc_lo, vcc_lo, 17
	s_add_u32 vcc_lo, s4, vcc_lo
	s_addc_u32 vcc_hi, s5, 0
	v_lshl_add_u64 v[132:133], v[132:133], 2, vcc
	global_store_dword v[132:133], v131, off
.LBB0_227:
	s_or_b64 exec, exec, s[36:37]
	v_add_u32_e32 v132, 0x80, v130
	v_ashrrev_i32_e32 v133, 31, v132
	s_waitcnt lgkmcnt(0)
	v_lshlrev_b64 v[136:137], 11, v[132:133]
	v_lshl_add_u64 v[140:141], v[128:129], 0, v[136:137]
	v_cvt_pk_bf16_f32 v136, v60, v61
	v_cvt_pk_bf16_f32 v137, v62, v63
	v_cvt_pk_bf16_f32 v138, v56, v57
	v_cvt_pk_bf16_f32 v139, v58, v59
	global_store_dwordx4 v[140:141], v[136:139], off
	v_mul_f32_e32 v131, v56, v56
	v_fmac_f32_e32 v131, v60, v60
	v_mul_f32_e32 v136, v57, v57
	v_fmac_f32_e32 v136, v61, v61
	v_add_f32_e32 v131, v131, v136
	v_mul_f32_e32 v136, v58, v58
	v_fmac_f32_e32 v136, v62, v62
	v_add_f32_e32 v131, v136, v131
	v_mul_f32_e32 v136, v59, v59
	v_fmac_f32_e32 v136, v63, v63
	v_add_f32_e32 v131, v136, v131
	v_cvt_pk_bf16_f32 v136, v48, v49
	v_cvt_pk_bf16_f32 v137, v50, v51
	v_cvt_pk_bf16_f32 v138, v40, v41
	v_cvt_pk_bf16_f32 v139, v42, v43
	global_store_dwordx4 v[140:141], v[136:139], off offset:256
	s_nop 1
	v_mul_f32_e32 v136, v40, v40
	v_fmac_f32_e32 v136, v48, v48
	v_add_f32_e32 v131, v131, v136
	v_mul_f32_e32 v136, v41, v41
	v_fmac_f32_e32 v136, v49, v49
	v_add_f32_e32 v131, v136, v131
	v_mul_f32_e32 v136, v42, v42
	v_fmac_f32_e32 v136, v50, v50
	v_add_f32_e32 v131, v136, v131
	v_mul_f32_e32 v136, v43, v43
	v_fmac_f32_e32 v136, v51, v51
	v_add_f32_e32 v131, v136, v131
	ds_bpermute_b32 v136, v134, v131
	s_waitcnt lgkmcnt(0)
	v_add_f32_e32 v131, v131, v136
	ds_bpermute_b32 v136, v135, v131
	s_and_saveexec_b64 s[36:37], s[40:41]
	s_cbranch_execz .LBB0_229
	s_waitcnt lgkmcnt(0)
	v_add_f32_e32 v131, v131, v136
	s_bfe_u32 vcc_lo, s79, 0x20006
	s_lshl2_add_u32 vcc_lo, s48, vcc_lo
	s_lshl_b32 vcc_lo, vcc_lo, 17
	s_add_u32 vcc_lo, s4, vcc_lo
	s_addc_u32 vcc_hi, s5, 0
	v_lshl_add_u64 v[132:133], v[132:133], 2, vcc
	global_store_dword v[132:133], v131, off
;     __device__ __forceinline__ void operator()(const f32x4 (&acc)[2][2][4][2], const Unit& u, int wr, int wc, int fr, int fq, const LAS float* rsl) const {
;     ...
;             for (int m = 0; m < 4; ++m) { const int row = row0 + ai * 128 + m * 16; bf16_t* rp = O + (size_t)row * 1024 + col0; float s = 0.f;
; #pragma unroll
;                 for (int bj = 0; bj < 2; ++bj) { const f32x4 v0 = acc[ai][bj][m][0], v1 = acc[ai][bj][m][1]; store8bf(rp + bj * 128, v0, v1);
; #pragma unroll
;                     for (int j = 0; j < 4; ++j) s += v0[j] * v0[j] + v1[j] * v1[j]; }
;                 s += __shfl_xor(s, 16); s += __shfl_xor(s, 32);
;                 if (fq == 0) atomicAdd(ssq + row, s);
;                 if (m & 1) asm volatile("" ::: "memory"); }
.LBB0_229:
	s_or_b64 exec, exec, s[36:37]
	v_add_u32_e32 v132, 0x90, v130
	v_ashrrev_i32_e32 v133, 31, v132
	s_waitcnt lgkmcnt(0)
	v_lshlrev_b64 v[136:137], 11, v[132:133]
	v_lshl_add_u64 v[140:141], v[128:129], 0, v[136:137]
	v_cvt_pk_bf16_f32 v136, v52, v53
	v_cvt_pk_bf16_f32 v137, v54, v55
	v_cvt_pk_bf16_f32 v138, v44, v45
	v_cvt_pk_bf16_f32 v139, v46, v47
	global_store_dwordx4 v[140:141], v[136:139], off
	v_mul_f32_e32 v131, v44, v44
	v_fmac_f32_e32 v131, v52, v52
	v_mul_f32_e32 v136, v45, v45
	v_fmac_f32_e32 v136, v53, v53
	v_add_f32_e32 v131, v131, v136
	v_mul_f32_e32 v136, v46, v46
	v_fmac_f32_e32 v136, v54, v54
	v_add_f32_e32 v131, v136, v131
	v_mul_f32_e32 v136, v47, v47
	v_fmac_f32_e32 v136, v55, v55
	v_add_f32_e32 v131, v136, v131
	v_cvt_pk_bf16_f32 v136, v32, v33
	v_cvt_pk_bf16_f32 v137, v34, v35
	v_cvt_pk_bf16_f32 v138, v24, v25
	v_cvt_pk_bf16_f32 v139, v26, v27
	global_store_dwordx4 v[140:141], v[136:139], off offset:256
	s_nop 1
	v_mul_f32_e32 v136, v24, v24
	v_fmac_f32_e32 v136, v32, v32
	v_add_f32_e32 v131, v131, v136
	v_mul_f32_e32 v136, v25, v25
	v_fmac_f32_e32 v136, v33, v33
	v_add_f32_e32 v131, v136, v131
	v_mul_f32_e32 v136, v26, v26
	v_fmac_f32_e32 v136, v34, v34
	v_add_f32_e32 v131, v136, v131
	v_mul_f32_e32 v136, v27, v27
	v_fmac_f32_e32 v136, v35, v35
	v_add_f32_e32 v131, v136, v131
	ds_bpermute_b32 v136, v134, v131
	s_waitcnt lgkmcnt(0)
	v_add_f32_e32 v131, v131, v136
	ds_bpermute_b32 v136, v135, v131
	s_and_saveexec_b64 s[36:37], s[40:41]
	s_cbranch_execz .LBB0_231
	s_waitcnt lgkmcnt(0)
	v_add_f32_e32 v131, v131, v136
	s_bfe_u32 vcc_lo, s79, 0x20006
	s_lshl2_add_u32 vcc_lo, s48, vcc_lo
	s_lshl_b32 vcc_lo, vcc_lo, 17
	s_add_u32 vcc_lo, s4, vcc_lo
	s_addc_u32 vcc_hi, s5, 0
	v_lshl_add_u64 v[132:133], v[132:133], 2, vcc
	global_store_dword v[132:133], v131, off
.LBB0_231:
	s_or_b64 exec, exec, s[36:37]
	v_add_u32_e32 v132, 0xa0, v130
	v_ashrrev_i32_e32 v133, 31, v132
	s_waitcnt lgkmcnt(0)
	v_lshlrev_b64 v[136:137], 11, v[132:133]
	v_lshl_add_u64 v[140:141], v[128:129], 0, v[136:137]
	v_cvt_pk_bf16_f32 v136, v36, v37
	v_cvt_pk_bf16_f32 v137, v38, v39
	v_cvt_pk_bf16_f32 v138, v28, v29
	v_cvt_pk_bf16_f32 v139, v30, v31
	global_store_dwordx4 v[140:141], v[136:139], off
	v_mul_f32_e32 v131, v28, v28
	v_fmac_f32_e32 v131, v36, v36
	v_mul_f32_e32 v136, v29, v29
	v_fmac_f32_e32 v136, v37, v37
	v_add_f32_e32 v131, v131, v136
	v_mul_f32_e32 v136, v30, v30
	v_fmac_f32_e32 v136, v38, v38
	v_add_f32_e32 v131, v136, v131
	v_mul_f32_e32 v136, v31, v31
	v_fmac_f32_e32 v136, v39, v39
	v_add_f32_e32 v131, v136, v131
	v_cvt_pk_bf16_f32 v136, v16, v17
	v_cvt_pk_bf16_f32 v137, v18, v19
	v_cvt_pk_bf16_f32 v138, v8, v9
	v_cvt_pk_bf16_f32 v139, v10, v11
	global_store_dwordx4 v[140:141], v[136:139], off offset:256
	s_nop 1
	v_mul_f32_e32 v136, v8, v8
	v_fmac_f32_e32 v136, v16, v16
	v_add_f32_e32 v131, v131, v136
	v_mul_f32_e32 v136, v9, v9
	v_fmac_f32_e32 v136, v17, v17
	v_add_f32_e32 v131, v136, v131
	v_mul_f32_e32 v136, v10, v10
	v_fmac_f32_e32 v136, v18, v18
	v_add_f32_e32 v131, v136, v131
	v_mul_f32_e32 v136, v11, v11
	v_fmac_f32_e32 v136, v19, v19
	v_add_f32_e32 v131, v136, v131
	ds_bpermute_b32 v136, v134, v131
	s_waitcnt lgkmcnt(0)
	v_add_f32_e32 v131, v131, v136
	ds_bpermute_b32 v136, v135, v131
	s_and_saveexec_b64 s[36:37], s[40:41]
	s_cbranch_execz .LBB0_233
	s_waitcnt lgkmcnt(0)
	v_add_f32_e32 v131, v131, v136
	s_bfe_u32 vcc_lo, s79, 0x20006
	s_lshl2_add_u32 vcc_lo, s48, vcc_lo
	s_lshl_b32 vcc_lo, vcc_lo, 17
	s_add_u32 vcc_lo, s4, vcc_lo
	s_addc_u32 vcc_hi, s5, 0
	v_lshl_add_u64 v[132:133], v[132:133], 2, vcc
	global_store_dword v[132:133], v131, off
.LBB0_233:
	s_or_b64 exec, exec, s[36:37]
	v_add_u32_e32 v130, 0xb0, v130
	v_ashrrev_i32_e32 v131, 31, v130
	v_lshlrev_b64 v[132:133], 11, v[130:131]
	v_lshl_add_u64 v[140:141], v[128:129], 0, v[132:133]
	v_mul_f32_e32 v128, v12, v12
	v_mul_f32_e32 v129, v13, v13
	v_fmac_f32_e32 v128, v20, v20
	v_fmac_f32_e32 v129, v21, v21
	v_add_f32_e32 v128, v128, v129
	v_mul_f32_e32 v129, v14, v14
	v_fmac_f32_e32 v129, v22, v22
	v_add_f32_e32 v128, v129, v128
	v_mul_f32_e32 v129, v15, v15
	v_fmac_f32_e32 v129, v23, v23
	v_add_f32_e32 v128, v129, v128
	v_mul_f32_e32 v129, v0, v0
	v_fmac_f32_e32 v129, v4, v4
	v_add_f32_e32 v128, v128, v129
	v_mul_f32_e32 v129, v1, v1
	v_fmac_f32_e32 v129, v5, v5
	v_add_f32_e32 v128, v129, v128
	v_mul_f32_e32 v129, v2, v2
	v_fmac_f32_e32 v129, v6, v6
	v_add_f32_e32 v128, v129, v128
	v_mul_f32_e32 v129, v3, v3
	v_fmac_f32_e32 v129, v7, v7
	v_add_f32_e32 v128, v129, v128
	ds_bpermute_b32 v129, v134, v128
	s_waitcnt lgkmcnt(0)
	v_cvt_pk_bf16_f32 v136, v20, v21
	v_cvt_pk_bf16_f32 v137, v22, v23
	v_cvt_pk_bf16_f32 v138, v12, v13
	v_cvt_pk_bf16_f32 v139, v14, v15
	v_add_f32_e32 v128, v128, v129
	ds_bpermute_b32 v129, v135, v128
	global_store_dwordx4 v[140:141], v[136:139], off
	v_cvt_pk_bf16_f32 v132, v4, v5
	v_cvt_pk_bf16_f32 v133, v6, v7
	v_cvt_pk_bf16_f32 v134, v0, v1
	v_cvt_pk_bf16_f32 v135, v2, v3
	global_store_dwordx4 v[140:141], v[132:135], off offset:256
	s_and_saveexec_b64 s[36:37], s[40:41]
	s_cbranch_execz .LBB0_235
	s_waitcnt lgkmcnt(0)
	v_add_f32_e32 v132, v128, v129
	s_bfe_u32 vcc_lo, s79, 0x20006
	s_lshl2_add_u32 vcc_lo, s48, vcc_lo
	s_lshl_b32 vcc_lo, vcc_lo, 17
	s_add_u32 vcc_lo, s4, vcc_lo
	s_addc_u32 vcc_hi, s5, 0
	v_lshl_add_u64 v[128:129], v[130:131], 2, vcc
	global_store_dword v[128:129], v132, off

; __global__ void __launch_bounds__(512, 2) fwd_megakernel(Params Pval) {
;     ...
;         if (ph + 1 < ph_hi) { if (ph_lo != 0) grid.sync(); else xcd_barrier(xbar); }
.LBB0_534:
	v_readlane_b32 s4, v255, 40
	s_cmp_lg_u32 s39, 7
	s_cbranch_scc1 .Lmini_inc
	s_cmp_lg_u32 s4, 0
	s_cbranch_scc1 .Lmini_inc
	s_mov_b32 s4, 1
	s_nop 0
	v_writelane_b32 v255, s4, 40
	s_add_i32 s39, s39, -1
